# PLE_1 epilogue rewritten by hand: all row loads in flight early (ring of register buffers + finished accumulator quads), packed f32 sigmoid/fma, counted vmcnt
# baseline (speedup 1.0000x reference)
; #define G_STAGE(bufoff, gbase, o0, h64) do { \
;         __builtin_amdgcn_global_load_lds((const unsigned*)((const char*)(gbase) + (o0)), (LAS unsigned*)(lds + (bufoff) + ldsw), 16, 0, 0); \
;         __builtin_amdgcn_global_load_lds((const unsigned*)((const char*)(gbase) + (h64) + (o0)), (LAS unsigned*)(lds + (bufoff) + ldsw + 8192), 16, 0, 0); } while (0)
; #define G_LDA(dst, b, h) do { _Pragma("unroll") for (int m = 0; m < 4; ++m) _Pragma("unroll") for (int k = 0; k < 2; ++k) dst[m][k] = *(const LAS bf16x8*)(lds + G_SA(b, h) + aoff + m * 2048 + k * 1024); } while (0)
; #define G_LDB(dst, b, h) do { _Pragma("unroll") for (int n = 0; n < 2; ++n) _Pragma("unroll") for (int k = 0; k < 2; ++k) dst[n][k] = *(const LAS bf16x8*)(lds + G_SB(b, h) + boff + n * 2048 + k * 1024); } while (0)
; #define G_WAIT_V(n) asm volatile("s_waitcnt vmcnt(" #n ")" ::: "memory")
; #define G_WAIT_L(n) asm volatile("s_waitcnt lgkmcnt(" #n ")" ::: "memory")
; #define G_BAR __builtin_amdgcn_s_barrier()
; #define G_SCHED __builtin_amdgcn_sched_barrier(0)
;     ...
;         for (int t = 0; t < nt; t += 2) {
;             const bool last = (t == nt - 2);
;             const char* a1 = cA + (size_t)(t + 1) * ckA;
;             const char* a2 = last ? nA : cA + (size_t)(t + 2) * ckA; const char* b2 = last ? nB : cB + (size_t)(t + 2) * kB;
;             const char* a3 = a2 + ckA; const char* b3 = b2 + kB;
;             G_LDB(B0, 0, 0); G_SCHED; G_LDA(At, 0, 0); G_STAGE(G_SA(1, 1), a1 + chA, cA0, qA);
;             G_WAIT_L(8); G_BAR; G_WAIT_L(0); G_MMA(0, 0, At, B0); G_BAR; G_SCHED;
;             G_LDB(B1, 0, 1); G_STAGE(G_SB(0, 0), b2, cB0, qB);
;             G_BAR; G_WAIT_L(0); G_MMA(0, 1, At, B1); G_BAR;
;             G_LDA(At, 0, 1); G_STAGE(G_SA(0, 0), a2, cA0, qA);
;             G_BAR; G_WAIT_L(0); G_MMA(1, 0, At, B0); G_BAR; G_SCHED;
;             G_STAGE(G_SB(0, 1), b2 + chB, cB0, qB);
;             G_WAIT_V(6); G_BAR; G_MMA(1, 1, At, B1); G_BAR;
.LBB0_1283:
	s_add_u32 s4, s2, 0xfffc0080
	s_addc_u32 s5, s3, -1
	s_add_i32 s25, 0, 0x10000
	v_add_u32_e32 v0, s25, v181
	ds_read_b128 v[136:139], v0
	ds_read_b128 v[140:143], v0 offset:1024
	ds_read_b128 v[144:147], v0 offset:2048
	ds_read_b128 v[148:151], v0 offset:3072
	s_cmp_eq_u32 s24, 12
	s_cselect_b32 s5, s19, s5
	s_cselect_b32 s4, s18, s4
	s_cselect_b32 s41, s21, s23
	s_cselect_b32 s40, s20, s22
	v_lshl_add_u64 v[184:185], s[2:3], 0, v[158:159]
	s_add_i32 m0, s29, 0xc000
	ds_read_b128 v[152:155], v182
	ds_read_b128 v[160:163], v182 offset:1024
	ds_read_b128 v[164:167], v182 offset:2048
	ds_read_b128 v[172:175], v182 offset:3072
	ds_read_b128 v[176:179], v182 offset:4096
	ds_read_b128 v[196:199], v182 offset:5120
	ds_read_b128 v[200:203], v182 offset:6144
	ds_read_b128 v[204:207], v182 offset:7168
	global_load_lds_dwordx4 v[184:185], off
	v_lshl_add_u64 v[184:185], v[184:185], 0, s[0:1]
	s_add_i32 m0, s29, 0xe000
	s_nop 0
	global_load_lds_dwordx4 v[184:185], off
	s_waitcnt lgkmcnt(8)
	s_barrier
	s_waitcnt lgkmcnt(0)
	s_setprio 3
	s_waitcnt lgkmcnt(0)
	v_mfma_f32_16x16x32_bf16 v[132:135], v[136:139], v[152:155], v[132:135]
	v_mfma_f32_16x16x32_bf16 v[128:131], v[144:147], v[152:155], v[128:131]
	v_mfma_f32_16x16x32_bf16 v[116:119], v[136:139], v[164:167], v[116:119]
	v_mfma_f32_16x16x32_bf16 v[112:115], v[144:147], v[164:167], v[112:115]
	v_mfma_f32_16x16x32_bf16 v[100:103], v[136:139], v[176:179], v[100:103]
	v_mfma_f32_16x16x32_bf16 v[96:99], v[144:147], v[176:179], v[96:99]
	v_mfma_f32_16x16x32_bf16 v[84:87], v[136:139], v[200:203], v[84:87]
	v_mfma_f32_16x16x32_bf16 v[80:83], v[144:147], v[200:203], v[80:83]
	v_mfma_f32_16x16x32_bf16 v[132:135], v[140:143], v[160:163], v[132:135]
	v_mfma_f32_16x16x32_bf16 v[128:131], v[148:151], v[160:163], v[128:131]
	v_mfma_f32_16x16x32_bf16 v[116:119], v[140:143], v[172:175], v[116:119]
	v_mfma_f32_16x16x32_bf16 v[112:115], v[148:151], v[172:175], v[112:115]
	v_mfma_f32_16x16x32_bf16 v[100:103], v[140:143], v[196:199], v[100:103]
	v_mfma_f32_16x16x32_bf16 v[96:99], v[148:151], v[196:199], v[96:99]
	v_mfma_f32_16x16x32_bf16 v[84:87], v[140:143], v[204:207], v[84:87]
	v_mfma_f32_16x16x32_bf16 v[80:83], v[148:151], v[204:207], v[80:83]
	s_setprio 0
	s_barrier
	s_add_i32 s44, 0, 0x14000
	s_add_i32 s25, s25, s27
	v_add_u32_e32 v0, s44, v181
	v_lshl_add_u64 v[184:185], s[40:41], 0, v[156:157]
	s_mov_b32 m0, s25
	ds_read_b128 v[208:211], v0
	ds_read_b128 v[212:215], v0 offset:1024
	ds_read_b128 v[216:219], v0 offset:2048
	ds_read_b128 v[220:223], v0 offset:3072
	global_load_lds_dwordx4 v[184:185], off
	v_lshl_add_u64 v[224:225], v[184:185], 0, s[0:1]
	s_add_i32 m0, s25, 0x2000
	s_nop 0
	global_load_lds_dwordx4 v[224:225], off
	s_barrier
	s_waitcnt lgkmcnt(0)
	s_setprio 3
	s_waitcnt lgkmcnt(0)
	v_mfma_f32_16x16x32_bf16 v[124:127], v[208:211], v[152:155], v[124:127]
	v_mfma_f32_16x16x32_bf16 v[120:123], v[216:219], v[152:155], v[120:123]
	v_mfma_f32_16x16x32_bf16 v[108:111], v[208:211], v[164:167], v[108:111]
	v_mfma_f32_16x16x32_bf16 v[104:107], v[216:219], v[164:167], v[104:107]
	v_mfma_f32_16x16x32_bf16 v[92:95], v[208:211], v[176:179], v[92:95]
	v_mfma_f32_16x16x32_bf16 v[88:91], v[216:219], v[176:179], v[88:91]
	v_mfma_f32_16x16x32_bf16 v[76:79], v[208:211], v[200:203], v[76:79]
	v_mfma_f32_16x16x32_bf16 v[72:75], v[216:219], v[200:203], v[72:75]
	v_mfma_f32_16x16x32_bf16 v[124:127], v[212:215], v[160:163], v[124:127]
	v_mfma_f32_16x16x32_bf16 v[120:123], v[220:223], v[160:163], v[120:123]
	v_mfma_f32_16x16x32_bf16 v[108:111], v[212:215], v[172:175], v[108:111]
	v_mfma_f32_16x16x32_bf16 v[104:107], v[220:223], v[172:175], v[104:107]
	v_mfma_f32_16x16x32_bf16 v[92:95], v[212:215], v[196:199], v[92:95]
	v_mfma_f32_16x16x32_bf16 v[88:91], v[220:223], v[196:199], v[88:91]
	v_mfma_f32_16x16x32_bf16 v[76:79], v[212:215], v[204:207], v[76:79]
	v_mfma_f32_16x16x32_bf16 v[72:75], v[220:223], v[204:207], v[72:75]
	s_setprio 0
	s_mov_b32 m0, s29
	v_lshl_add_u64 v[224:225], s[4:5], 0, v[2:3]
	s_barrier
	ds_read_b128 v[152:155], v182 offset:16384
	ds_read_b128 v[160:163], v182 offset:17408
	ds_read_b128 v[164:167], v182 offset:18432
	ds_read_b128 v[172:175], v182 offset:19456
	ds_read_b128 v[176:179], v182 offset:20480
	ds_read_b128 v[196:199], v182 offset:21504
	ds_read_b128 v[200:203], v182 offset:22528
	ds_read_b128 v[204:207], v182 offset:23552
	global_load_lds_dwordx4 v[224:225], off
	v_lshl_add_u64 v[226:227], v[224:225], 0, s[0:1]
	s_mov_b32 m0, s30
	s_nop 0
	global_load_lds_dwordx4 v[226:227], off
	s_barrier
	s_waitcnt lgkmcnt(0)
	s_setprio 3
	s_waitcnt lgkmcnt(0)
	v_mfma_f32_16x16x32_bf16 v[68:71], v[136:139], v[152:155], v[68:71]
	v_mfma_f32_16x16x32_bf16 v[64:67], v[144:147], v[152:155], v[64:67]
	v_mfma_f32_16x16x32_bf16 v[52:55], v[136:139], v[164:167], v[52:55]
	v_mfma_f32_16x16x32_bf16 v[48:51], v[144:147], v[164:167], v[48:51]
	v_mfma_f32_16x16x32_bf16 v[36:39], v[136:139], v[176:179], v[36:39]
	v_mfma_f32_16x16x32_bf16 v[32:35], v[144:147], v[176:179], v[32:35]
	v_mfma_f32_16x16x32_bf16 v[20:23], v[136:139], v[200:203], v[20:23]
	v_mfma_f32_16x16x32_bf16 v[16:19], v[144:147], v[200:203], v[16:19]
	v_mfma_f32_16x16x32_bf16 v[68:71], v[140:143], v[160:163], v[68:71]
	v_mfma_f32_16x16x32_bf16 v[64:67], v[148:151], v[160:163], v[64:67]
	v_mfma_f32_16x16x32_bf16 v[52:55], v[140:143], v[172:175], v[52:55]
	v_mfma_f32_16x16x32_bf16 v[48:51], v[148:151], v[172:175], v[48:51]
	v_mfma_f32_16x16x32_bf16 v[36:39], v[140:143], v[196:199], v[36:39]
	v_mfma_f32_16x16x32_bf16 v[32:35], v[148:151], v[196:199], v[32:35]
	v_mfma_f32_16x16x32_bf16 v[20:23], v[140:143], v[204:207], v[20:23]
	v_mfma_f32_16x16x32_bf16 v[16:19], v[148:151], v[204:207], v[16:19]
	s_setprio 0
	s_barrier
; #define G_STAGE(bufoff, gbase, o0, h64) do { \
;         __builtin_amdgcn_global_load_lds((const unsigned*)((const char*)(gbase) + (o0)), (LAS unsigned*)(lds + (bufoff) + ldsw), 16, 0, 0); \
;         __builtin_amdgcn_global_load_lds((const unsigned*)((const char*)(gbase) + (h64) + (o0)), (LAS unsigned*)(lds + (bufoff) + ldsw + 8192), 16, 0, 0); } while (0)
; #define G_LDA(dst, b, h) do { _Pragma("unroll") for (int m = 0; m < 4; ++m) _Pragma("unroll") for (int k = 0; k < 2; ++k) dst[m][k] = *(const LAS bf16x8*)(lds + G_SA(b, h) + aoff + m * 2048 + k * 1024); } while (0)
; #define G_LDB(dst, b, h) do { _Pragma("unroll") for (int n = 0; n < 2; ++n) _Pragma("unroll") for (int k = 0; k < 2; ++k) dst[n][k] = *(const LAS bf16x8*)(lds + G_SB(b, h) + boff + n * 2048 + k * 1024); } while (0)
; #define G_WAIT_V(n) asm volatile("s_waitcnt vmcnt(" #n ")" ::: "memory")
; #define G_WAIT_L(n) asm volatile("s_waitcnt lgkmcnt(" #n ")" ::: "memory")
; #define G_BAR __builtin_amdgcn_s_barrier()
; #define G_SCHED __builtin_amdgcn_sched_barrier(0)
;     ...
;             G_STAGE(G_SB(0, 1), b2 + chB, cB0, qB);
;             G_WAIT_V(6); G_BAR; G_MMA(1, 1, At, B1); G_BAR;
;             G_LDB(B0, 1, 0); G_SCHED; G_LDA(At, 1, 0); G_STAGE(G_SA(0, 1), a2 + chA, cA0, qA);
;             G_WAIT_L(8); G_BAR; G_WAIT_L(0); G_MMA(0, 0, At, B0); G_BAR; G_SCHED;
;             G_LDB(B1, 1, 1); G_STAGE(G_SB(1, 0), b3, cB0, qB);
;             G_BAR; G_WAIT_L(0); G_MMA(0, 1, At, B1); G_BAR;
;             G_LDA(At, 1, 1); G_STAGE(G_SA(1, 0), a3, cA0, qA);
;             G_BAR; G_WAIT_L(0); G_MMA(1, 0, At, B0); G_BAR; G_SCHED;
	s_add_i32 s4, s44, s27
	v_lshl_add_u64 v[136:137], v[184:185], 0, s[54:55]
	s_mov_b32 m0, s4
	s_nop 0
	global_load_lds_dwordx4 v[136:137], off
	v_lshl_add_u64 v[136:137], v[184:185], 0, s[58:59]
	s_add_i32 m0, s4, 0x2000
	s_nop 0
	global_load_lds_dwordx4 v[136:137], off
	s_waitcnt vmcnt(6)
	s_barrier
	s_setprio 3
	v_mfma_f32_16x16x32_bf16 v[60:63], v[208:211], v[152:155], v[60:63]
	v_mfma_f32_16x16x32_bf16 v[56:59], v[216:219], v[152:155], v[56:59]
	v_mfma_f32_16x16x32_bf16 v[44:47], v[208:211], v[164:167], v[44:47]
	v_mfma_f32_16x16x32_bf16 v[40:43], v[216:219], v[164:167], v[40:43]
	v_mfma_f32_16x16x32_bf16 v[28:31], v[208:211], v[176:179], v[28:31]
	v_mfma_f32_16x16x32_bf16 v[24:27], v[216:219], v[176:179], v[24:27]
	v_mfma_f32_16x16x32_bf16 v[12:15], v[208:211], v[200:203], v[12:15]
	v_mfma_f32_16x16x32_bf16 v[8:11], v[216:219], v[200:203], v[8:11]
	v_mfma_f32_16x16x32_bf16 v[60:63], v[212:215], v[160:163], v[60:63]
	v_mfma_f32_16x16x32_bf16 v[56:59], v[220:223], v[160:163], v[56:59]
	v_mfma_f32_16x16x32_bf16 v[44:47], v[212:215], v[172:175], v[44:47]
	v_mfma_f32_16x16x32_bf16 v[40:43], v[220:223], v[172:175], v[40:43]
	v_mfma_f32_16x16x32_bf16 v[28:31], v[212:215], v[196:199], v[28:31]
	v_mfma_f32_16x16x32_bf16 v[24:27], v[220:223], v[196:199], v[24:27]
	v_mfma_f32_16x16x32_bf16 v[12:15], v[212:215], v[204:207], v[12:15]
	v_mfma_f32_16x16x32_bf16 v[8:11], v[220:223], v[204:207], v[8:11]
	s_setprio 0
	s_add_i32 s4, 0, 0x18000
	v_add_u32_e32 v0, s4, v181
	s_barrier
	ds_read_b128 v[136:139], v0
	ds_read_b128 v[140:143], v0 offset:1024
	ds_read_b128 v[144:147], v0 offset:2048
	ds_read_b128 v[148:151], v0 offset:3072
	s_mov_b32 m0, s31
	v_lshl_add_u64 v[208:209], v[224:225], 0, s[54:55]
	ds_read_b128 v[152:155], v182 offset:32768
	ds_read_b128 v[160:163], v182 offset:33792
	ds_read_b128 v[164:167], v182 offset:34816
	ds_read_b128 v[172:175], v182 offset:35840
	ds_read_b128 v[176:179], v182 offset:36864
	ds_read_b128 v[196:199], v182 offset:37888
	ds_read_b128 v[200:203], v182 offset:38912
	ds_read_b128 v[204:207], v182 offset:39936
	global_load_lds_dwordx4 v[208:209], off
	v_lshl_add_u64 v[208:209], v[224:225], 0, s[58:59]
	s_mov_b32 m0, s34
	s_nop 0
	global_load_lds_dwordx4 v[208:209], off
	s_waitcnt lgkmcnt(8)
	s_barrier
	s_waitcnt lgkmcnt(0)
	s_setprio 3
	s_waitcnt lgkmcnt(0)
	v_mfma_f32_16x16x32_bf16 v[132:135], v[136:139], v[152:155], v[132:135]
	v_mfma_f32_16x16x32_bf16 v[128:131], v[144:147], v[152:155], v[128:131]
	v_mfma_f32_16x16x32_bf16 v[116:119], v[136:139], v[164:167], v[116:119]
	v_mfma_f32_16x16x32_bf16 v[112:115], v[144:147], v[164:167], v[112:115]
	v_mfma_f32_16x16x32_bf16 v[100:103], v[136:139], v[176:179], v[100:103]
	v_mfma_f32_16x16x32_bf16 v[96:99], v[144:147], v[176:179], v[96:99]
	v_mfma_f32_16x16x32_bf16 v[84:87], v[136:139], v[200:203], v[84:87]
	v_mfma_f32_16x16x32_bf16 v[80:83], v[144:147], v[200:203], v[80:83]
	v_mfma_f32_16x16x32_bf16 v[132:135], v[140:143], v[160:163], v[132:135]
	v_mfma_f32_16x16x32_bf16 v[128:131], v[148:151], v[160:163], v[128:131]
	v_mfma_f32_16x16x32_bf16 v[116:119], v[140:143], v[172:175], v[116:119]
	v_mfma_f32_16x16x32_bf16 v[112:115], v[148:151], v[172:175], v[112:115]
	v_mfma_f32_16x16x32_bf16 v[100:103], v[140:143], v[196:199], v[100:103]
	v_mfma_f32_16x16x32_bf16 v[96:99], v[148:151], v[196:199], v[96:99]
	v_mfma_f32_16x16x32_bf16 v[84:87], v[140:143], v[204:207], v[84:87]
	v_mfma_f32_16x16x32_bf16 v[80:83], v[148:151], v[204:207], v[80:83]
	s_setprio 0
	s_barrier
	s_add_i32 s5, 0, 0x1c000
	s_add_i32 s4, s4, s27
	v_add_u32_e32 v0, s5, v181
	v_lshl_add_u64 v[226:227], v[184:185], 0, s[46:47]
	s_mov_b32 m0, s4
	ds_read_b128 v[208:211], v0
	ds_read_b128 v[212:215], v0 offset:1024
	ds_read_b128 v[216:219], v0 offset:2048
	ds_read_b128 v[220:223], v0 offset:3072
	global_load_lds_dwordx4 v[226:227], off
	v_lshl_add_u64 v[226:227], v[184:185], 0, s[62:63]
	s_add_i32 m0, s4, 0x2000
	s_nop 0
	global_load_lds_dwordx4 v[226:227], off
	s_barrier
	s_waitcnt lgkmcnt(0)
	s_setprio 3
	s_waitcnt lgkmcnt(0)
	v_mfma_f32_16x16x32_bf16 v[124:127], v[208:211], v[152:155], v[124:127]
	v_mfma_f32_16x16x32_bf16 v[120:123], v[216:219], v[152:155], v[120:123]
	v_mfma_f32_16x16x32_bf16 v[108:111], v[208:211], v[164:167], v[108:111]
	v_mfma_f32_16x16x32_bf16 v[104:107], v[216:219], v[164:167], v[104:107]
	v_mfma_f32_16x16x32_bf16 v[92:95], v[208:211], v[176:179], v[92:95]
	v_mfma_f32_16x16x32_bf16 v[88:91], v[216:219], v[176:179], v[88:91]
	v_mfma_f32_16x16x32_bf16 v[76:79], v[208:211], v[200:203], v[76:79]
	v_mfma_f32_16x16x32_bf16 v[72:75], v[216:219], v[200:203], v[72:75]
	v_mfma_f32_16x16x32_bf16 v[124:127], v[212:215], v[160:163], v[124:127]
	v_mfma_f32_16x16x32_bf16 v[120:123], v[220:223], v[160:163], v[120:123]
	v_mfma_f32_16x16x32_bf16 v[108:111], v[212:215], v[172:175], v[108:111]
	v_mfma_f32_16x16x32_bf16 v[104:107], v[220:223], v[172:175], v[104:107]
	v_mfma_f32_16x16x32_bf16 v[92:95], v[212:215], v[196:199], v[92:95]
	v_mfma_f32_16x16x32_bf16 v[88:91], v[220:223], v[196:199], v[88:91]
	v_mfma_f32_16x16x32_bf16 v[76:79], v[212:215], v[204:207], v[76:79]
	v_mfma_f32_16x16x32_bf16 v[72:75], v[220:223], v[204:207], v[72:75]
	s_setprio 0
	s_mov_b32 m0, s35
	v_lshl_add_u64 v[226:227], v[224:225], 0, s[46:47]
	s_barrier
	ds_read_b128 v[152:155], v182 offset:49152
	ds_read_b128 v[160:163], v182 offset:50176
	ds_read_b128 v[164:167], v182 offset:51200
	ds_read_b128 v[172:175], v182 offset:52224
	ds_read_b128 v[176:179], v182 offset:53248
	ds_read_b128 v[196:199], v182 offset:54272
	ds_read_b128 v[200:203], v182 offset:55296
	ds_read_b128 v[204:207], v182 offset:56320
	global_load_lds_dwordx4 v[226:227], off
	v_lshl_add_u64 v[224:225], v[224:225], 0, s[62:63]
	s_mov_b32 m0, s36
	s_nop 0
	global_load_lds_dwordx4 v[224:225], off
	s_barrier
; #define G_STAGE(bufoff, gbase, o0, h64) do { \
;         __builtin_amdgcn_global_load_lds((const unsigned*)((const char*)(gbase) + (o0)), (LAS unsigned*)(lds + (bufoff) + ldsw), 16, 0, 0); \
;         __builtin_amdgcn_global_load_lds((const unsigned*)((const char*)(gbase) + (h64) + (o0)), (LAS unsigned*)(lds + (bufoff) + ldsw + 8192), 16, 0, 0); } while (0)
; #define G_LDA(dst, b, h) do { _Pragma("unroll") for (int m = 0; m < 4; ++m) _Pragma("unroll") for (int k = 0; k < 2; ++k) dst[m][k] = *(const LAS bf16x8*)(lds + G_SA(b, h) + aoff + m * 2048 + k * 1024); } while (0)
; #define G_WAIT_V(n) asm volatile("s_waitcnt vmcnt(" #n ")" ::: "memory")
; #define G_WAIT_L(n) asm volatile("s_waitcnt lgkmcnt(" #n ")" ::: "memory")
; #define G_BAR __builtin_amdgcn_s_barrier()
; #define G_SCHED __builtin_amdgcn_sched_barrier(0)
;     template <int KIND> __device__ __forceinline__ void run(f32x4 (&acc)[2][2][4][2], const Unit& u, int tid_in) const {
;     ...
;         if constexpr (KIND == K_PLE) {
;             const bf16_t* xsrc = mg; float rs[8]; get_rs(u, wr, fr, rs);
; #pragma unroll
;             for (int ai = 0; ai < 2; ++ai)
; #pragma unroll
;                 for (int mh = 0; mh < 2; ++mh) { u32x4 xv[2][2], pv[2][2];
; #pragma unroll
;                     for (int ml = 0; ml < 2; ++ml) { const int m = mh * 2 + ml; int row = rbase + ai * 128 + m * 16; asm volatile("" : "+v"(row));
; #pragma unroll
;                         for (int bj = 0; bj < 2; ++bj) { xv[ml][bj] = *(const u32x4*)(xsrc + (size_t)row * 1024 + u.pn * 256 + bj * 128 + cl); pv[ml][bj] = scr[((ai * 4 + m) * 2 + bj) * 512 + tid]; } }
;     ...
;             G_BAR; G_WAIT_L(0); G_MMA(0, 1, At, B1); G_BAR;
;             G_LDA(At, 1, 1); G_STAGE(G_SA(1, 0), a3, cA0, qA);
;             G_BAR; G_WAIT_L(0); G_MMA(1, 0, At, B0); G_BAR; G_SCHED;
;             G_STAGE(G_SB(1, 1), b3 + chB, cB0, qB);
;             G_WAIT_V(6); G_BAR; G_MMA(1, 1, At, B1); G_BAR;
;         }
	s_waitcnt lgkmcnt(0)
	s_setprio 3
	s_waitcnt lgkmcnt(0)
	v_mfma_f32_16x16x32_bf16 v[68:71], v[136:139], v[152:155], v[68:71]
	v_mfma_f32_16x16x32_bf16 v[64:67], v[144:147], v[152:155], v[64:67]
	v_mfma_f32_16x16x32_bf16 v[52:55], v[136:139], v[164:167], v[52:55]
	v_mfma_f32_16x16x32_bf16 v[48:51], v[144:147], v[164:167], v[48:51]
	v_mfma_f32_16x16x32_bf16 v[36:39], v[136:139], v[176:179], v[36:39]
	v_mfma_f32_16x16x32_bf16 v[32:35], v[144:147], v[176:179], v[32:35]
	v_mfma_f32_16x16x32_bf16 v[20:23], v[136:139], v[200:203], v[20:23]
	v_mfma_f32_16x16x32_bf16 v[16:19], v[144:147], v[200:203], v[16:19]
	v_mfma_f32_16x16x32_bf16 v[68:71], v[140:143], v[160:163], v[68:71]
	v_mfma_f32_16x16x32_bf16 v[64:67], v[148:151], v[160:163], v[64:67]
	v_mfma_f32_16x16x32_bf16 v[52:55], v[140:143], v[172:175], v[52:55]
	v_mfma_f32_16x16x32_bf16 v[48:51], v[148:151], v[172:175], v[48:51]
	v_mfma_f32_16x16x32_bf16 v[36:39], v[140:143], v[196:199], v[36:39]
	v_mfma_f32_16x16x32_bf16 v[32:35], v[148:151], v[196:199], v[32:35]
	v_mfma_f32_16x16x32_bf16 v[20:23], v[140:143], v[204:207], v[20:23]
	v_mfma_f32_16x16x32_bf16 v[16:19], v[148:151], v[204:207], v[16:19]
	s_setprio 0
	s_barrier
	s_add_i32 s4, s5, s27
	v_lshl_add_u64 v[136:137], v[184:185], 0, s[64:65]
	s_mov_b32 m0, s4
	s_nop 0
	global_load_lds_dwordx4 v[136:137], off
	v_lshl_add_u64 v[136:137], v[184:185], 0, s[66:67]
	s_add_i32 m0, s4, 0x2000
	s_nop 0
	global_load_lds_dwordx4 v[136:137], off
	s_waitcnt vmcnt(6)
	s_barrier
	s_setprio 3
	v_mfma_f32_16x16x32_bf16 v[60:63], v[208:211], v[152:155], v[60:63]
	v_mfma_f32_16x16x32_bf16 v[56:59], v[216:219], v[152:155], v[56:59]
	v_mfma_f32_16x16x32_bf16 v[44:47], v[208:211], v[164:167], v[44:47]
	v_mfma_f32_16x16x32_bf16 v[40:43], v[216:219], v[164:167], v[40:43]
	v_mfma_f32_16x16x32_bf16 v[28:31], v[208:211], v[176:179], v[28:31]
	v_mfma_f32_16x16x32_bf16 v[24:27], v[216:219], v[176:179], v[24:27]
	v_mfma_f32_16x16x32_bf16 v[12:15], v[208:211], v[200:203], v[12:15]
	v_mfma_f32_16x16x32_bf16 v[8:11], v[216:219], v[200:203], v[8:11]
	v_mfma_f32_16x16x32_bf16 v[60:63], v[212:215], v[160:163], v[60:63]
	v_mfma_f32_16x16x32_bf16 v[56:59], v[220:223], v[160:163], v[56:59]
	v_mfma_f32_16x16x32_bf16 v[44:47], v[212:215], v[172:175], v[44:47]
	v_mfma_f32_16x16x32_bf16 v[40:43], v[220:223], v[172:175], v[40:43]
	v_mfma_f32_16x16x32_bf16 v[28:31], v[212:215], v[196:199], v[28:31]
	v_mfma_f32_16x16x32_bf16 v[24:27], v[220:223], v[196:199], v[24:27]
	v_mfma_f32_16x16x32_bf16 v[12:15], v[212:215], v[204:207], v[12:15]
	v_mfma_f32_16x16x32_bf16 v[8:11], v[220:223], v[204:207], v[8:11]
	s_setprio 0
	s_add_i32 s24, s24, 2
	s_add_u32 s2, s2, 0x100
	s_addc_u32 s3, s3, 0
	s_add_u32 s22, s22, 0x100
	s_addc_u32 s23, s23, 0
	s_cmp_gt_u32 s24, 13
	s_barrier
	s_cbranch_scc0 .LBB0_1283
	s_lshl_b32 s2, s33, 17
	s_and_b32 s2, s2, 0x20000
	s_add_u32 s22, s43, s2
	s_addc_u32 s23, s50, 0
	v_readfirstlane_b32 s4, v180
	s_bfe_u32 s53, s4, 0x20006
	s_lshl_b32 s5, s7, 8
	s_ashr_i32 s7, s4, 2
	s_andn2_b32 s7, s7, 63
	s_add_i32 s7, s7, s5
	s_lshl_b32 s5, s33, 10
	s_and_b32 s4, s4, 0xffffff00
	s_add_i32 s5, s5, s4
	v_and_b32_e32 v0, 15, v180
	v_or_b32_e32 v195, s7, v0
	v_lshl_add_u32 v0, v0, 2, s5
	v_add_u32_e32 v0, 0x20010, v0
	ds_read_b32 v250, v0
	ds_read_b32 v251, v0 offset:64
	ds_read_b32 v252, v0 offset:128
	ds_read_b32 v253, v0 offset:192
	ds_read_b32 v254, v0 offset:512
	ds_read_b32 v255, v0 offset:576
	ds_read_b32 v224, v0 offset:640
	ds_read_b32 v225, v0 offset:704
	v_bfe_u32 v226, v180, 4, 2
	v_lshlrev_b32_e32 v226, 3, v226
	v_lshl_or_b32 v226, s53, 5, v226
	s_lshl_b32 s2, s6, 8
	v_add_u32_e32 v226, s2, v226
	v_lshlrev_b32_e32 v183, 11, v195
	v_lshl_add_u32 v183, v226, 1, v183
	v_mad_u32_u24 v185, v195, s76, v226
	v_lshlrev_b32_e32 v184, 4, v180
	s_mov_b32 s4, s8
	s_mov_b32 s5, s9
	s_mov_b32 s24, s22
	s_mov_b32 s25, s23
	global_load_dwordx4 v[136:139], v183, s[4:5]
	global_load_dwordx4 v[144:147], v184, s[24:25]
	s_add_u32 s24, s24, 0x2000
	s_addc_u32 s25, s25, 0
	global_load_dwordx4 v[140:143], v183, s[4:5] offset:256
	global_load_dwordx4 v[148:151], v184, s[24:25]
	s_add_u32 s4, s8, 0x8000
	s_addc_u32 s5, s9, 0
	s_add_u32 s24, s22, 0x4000
	s_addc_u32 s25, s23, 0
	global_load_dwordx4 v[152:155], v183, s[4:5]
	global_load_dwordx4 v[164:167], v184, s[24:25]
	s_add_u32 s24, s24, 0x2000
	s_addc_u32 s25, s25, 0
	global_load_dwordx4 v[160:163], v183, s[4:5] offset:256
	global_load_dwordx4 v[172:175], v184, s[24:25]
	s_add_u32 s4, s8, 0x10000
	s_addc_u32 s5, s9, 0
	s_add_u32 s24, s22, 0x8000
	s_addc_u32 s25, s23, 0
	global_load_dwordx4 v[176:179], v183, s[4:5]
	global_load_dwordx4 v[200:203], v184, s[24:25]
	s_add_u32 s24, s24, 0x2000
	s_addc_u32 s25, s25, 0
	global_load_dwordx4 v[196:199], v183, s[4:5] offset:256
	global_load_dwordx4 v[204:207], v184, s[24:25]
	s_add_u32 s4, s8, 0x18000
	s_addc_u32 s5, s9, 0
	s_add_u32 s24, s22, 0xc000
	s_addc_u32 s25, s23, 0
	global_load_dwordx4 v[208:211], v183, s[4:5]
	global_load_dwordx4 v[216:219], v184, s[24:25]
	s_add_u32 s24, s24, 0x2000
	s_addc_u32 s25, s25, 0
	global_load_dwordx4 v[212:215], v183, s[4:5] offset:256
	global_load_dwordx4 v[220:223], v184, s[24:25]
	s_mov_b32 s2, 0xbfb8aa3b
	s_mov_b32 s74, 1.0
	s_waitcnt lgkmcnt(0)
	s_waitcnt vmcnt(12)
; __device__ __forceinline__ float sigmoidf_(float v) { return __builtin_amdgcn_rcpf(1.0f + __expf(-v)); }
; __device__ __forceinline__ u32x4 pack8(const f32x4 a, const f32x4 b) { u32x4 w; w.x = cvt_pk_bf16(a[0], a[1]); w.y = cvt_pk_bf16(a[2], a[3]); w.z = cvt_pk_bf16(b[0], b[1]); w.w = cvt_pk_bf16(b[2], b[3]); return w; }
; __device__ __forceinline__ void unpack8(const u32x4 w, f32x4& a, f32x4& b) { a[0] = bf_lo(w.x); a[1] = bf_hi(w.x); a[2] = bf_lo(w.y); a[3] = bf_hi(w.y); b[0] = bf_lo(w.z); b[1] = bf_hi(w.z); b[2] = bf_lo(w.w); b[3] = bf_hi(w.w); }
; __device__ __forceinline__ unsigned pack4_fp8(float a, float b, float c, float d) { unsigned w = 0u; w = __builtin_amdgcn_cvt_pk_fp8_f32(a, b, w, false); w = __builtin_amdgcn_cvt_pk_fp8_f32(c, d, w, true); return w; }
;     template <int KIND> __device__ __forceinline__ void run(f32x4 (&acc)[2][2][4][2], const Unit& u, int tid_in) const {
;     ...
;                     for (int ml = 0; ml < 2; ++ml) { const int m = mh * 2 + ml; int row = rbase + ai * 128 + m * 16; asm volatile("" : "+v"(row)); float ss = 0.f; const float r = rs[ai * 4 + m];
; #pragma unroll
;                         for (int bj = 0; bj < 2; ++bj) { const size_t off = (size_t)row * 1024 + u.pn * 256 + bj * 128 + cl; f32x4 a = acc[ai][bj][m][0], b = acc[ai][bj][m][1], p0, p1, x0, x1;
;                             unpack8(pv[ml][bj], p0, p1); unpack8(xv[ml][bj], x0, x1);
; #pragma unroll
;                             for (int j = 0; j < 4; ++j) { a[j] = sigmoidf_(a[j] * r) * p0[j]; b[j] = sigmoidf_(b[j] * r) * p1[j]; }
;                             const f32x4 o0 = x0 + a, o1 = x1 + b;
;                             *(u32x4*)(xb0 + off) = pack8(o0, o1);
;                             { u32x2 w8; w8.x = pack4_fp8(o0[0], o0[1], o0[2], o0[3]); w8.y = pack4_fp8(o1[0], o1[1], o1[2], o1[3]); *(u32x2*)((unsigned char*)zb + (size_t)row * (ZW * 2) + u.pn * 256 + bj * 128 + cl) = w8; }
;                             ss += (o0[0] * o0[0] + o0[1] * o0[1]) + (o0[2] * o0[2] + o0[3] * o0[3]) + (o1[0] * o1[0] + o1[1] * o1[1]) + (o1[2] * o1[2] + o1[3] * o1[3]); }
;                         ss += __shfl_xor(ss, 16); ss += __shfl_xor(ss, 32);
;                         if (fq == 0) ssq0[((size_t)u.pn * T_TOK + row) * 4 + wc] = ss; }
	v_mov_b32_e32 v226, v250
	s_mov_b32 s40, s12
	s_mov_b32 s41, s13
	s_mov_b32 s44, s10
	s_mov_b32 s45, s11
	v_pk_mul_f32 v[132:133], v[132:133], v[226:227] op_sel_hi:[1,0]
	v_pk_mul_f32 v[134:135], v[134:135], v[226:227] op_sel_hi:[1,0]
	v_pk_mul_f32 v[128:129], v[128:129], v[226:227] op_sel_hi:[1,0]
	v_pk_mul_f32 v[130:131], v[130:131], v[226:227] op_sel_hi:[1,0]
	v_pk_mul_f32 v[132:133], v[132:133], s[2:3] op_sel_hi:[1,0]
	v_pk_mul_f32 v[134:135], v[134:135], s[2:3] op_sel_hi:[1,0]
	v_pk_mul_f32 v[128:129], v[128:129], s[2:3] op_sel_hi:[1,0]
	v_pk_mul_f32 v[130:131], v[130:131], s[2:3] op_sel_hi:[1,0]
	v_exp_f32_e32 v132, v132
	v_exp_f32_e32 v133, v133
	v_exp_f32_e32 v134, v134
	v_exp_f32_e32 v135, v135
	v_exp_f32_e32 v128, v128
	v_exp_f32_e32 v129, v129
	v_exp_f32_e32 v130, v130
	v_exp_f32_e32 v131, v131
	v_pk_add_f32 v[132:133], v[132:133], s[74:75] op_sel_hi:[1,0]
	v_pk_add_f32 v[134:135], v[134:135], s[74:75] op_sel_hi:[1,0]
	v_pk_add_f32 v[128:129], v[128:129], s[74:75] op_sel_hi:[1,0]
	v_pk_add_f32 v[130:131], v[130:131], s[74:75] op_sel_hi:[1,0]
	v_rcp_f32_e32 v132, v132
	v_rcp_f32_e32 v133, v133
	v_rcp_f32_e32 v134, v134
	v_rcp_f32_e32 v135, v135
	v_rcp_f32_e32 v128, v128
	v_rcp_f32_e32 v129, v129
	v_rcp_f32_e32 v130, v130
	v_rcp_f32_e32 v131, v131
	v_lshlrev_b32_e32 v234, 16, v136
	v_and_b32_e32 v235, 0xffff0000, v136
	v_lshlrev_b32_e32 v236, 16, v137
	v_and_b32_e32 v237, 0xffff0000, v137
	v_lshlrev_b32_e32 v238, 16, v138
	v_and_b32_e32 v239, 0xffff0000, v138
	v_lshlrev_b32_e32 v240, 16, v139
	v_and_b32_e32 v241, 0xffff0000, v139
	v_lshlrev_b32_e32 v242, 16, v144
	v_and_b32_e32 v243, 0xffff0000, v144
	v_lshlrev_b32_e32 v244, 16, v145
	v_and_b32_e32 v245, 0xffff0000, v145
	v_lshlrev_b32_e32 v246, 16, v146
	v_and_b32_e32 v247, 0xffff0000, v146
	v_lshlrev_b32_e32 v248, 16, v147
	v_and_b32_e32 v249, 0xffff0000, v147
	v_pk_fma_f32 v[132:133], v[132:133], v[242:243], v[234:235]
	v_pk_fma_f32 v[134:135], v[134:135], v[244:245], v[236:237]
	v_pk_fma_f32 v[128:129], v[128:129], v[246:247], v[238:239]
	v_pk_fma_f32 v[130:131], v[130:131], v[248:249], v[240:241]
	v_cvt_pk_bf16_f32 v234, v132, v133
	v_cvt_pk_bf16_f32 v235, v134, v135
	v_cvt_pk_bf16_f32 v236, v128, v129
	v_cvt_pk_bf16_f32 v237, v130, v131
	global_store_dwordx4 v183, v[234:237], s[40:41]
	v_cvt_pk_fp8_f32 v242, v132, v133
	v_cvt_pk_fp8_f32 v243, v128, v129
	v_cvt_pk_fp8_f32 v242, v134, v135 op_sel:[0,0,1]
	v_cvt_pk_fp8_f32 v243, v130, v131 op_sel:[0,0,1]
	v_pk_mul_f32 v[248:249], v[132:133], v[132:133]
	v_pk_fma_f32 v[248:249], v[134:135], v[134:135], v[248:249]
	v_pk_fma_f32 v[248:249], v[128:129], v[128:129], v[248:249]
	v_pk_fma_f32 v[248:249], v[130:131], v[130:131], v[248:249]
	global_store_dwordx2 v185, v[242:243], s[44:45]
	v_add_f32_e32 v195, v248, v249
	v_pk_mul_f32 v[124:125], v[124:125], v[226:227] op_sel_hi:[1,0]
	v_pk_mul_f32 v[126:127], v[126:127], v[226:227] op_sel_hi:[1,0]
	v_pk_mul_f32 v[120:121], v[120:121], v[226:227] op_sel_hi:[1,0]
	v_pk_mul_f32 v[122:123], v[122:123], v[226:227] op_sel_hi:[1,0]
	v_pk_mul_f32 v[124:125], v[124:125], s[2:3] op_sel_hi:[1,0]
	v_pk_mul_f32 v[126:127], v[126:127], s[2:3] op_sel_hi:[1,0]
	v_pk_mul_f32 v[120:121], v[120:121], s[2:3] op_sel_hi:[1,0]
	v_pk_mul_f32 v[122:123], v[122:123], s[2:3] op_sel_hi:[1,0]
	v_exp_f32_e32 v124, v124
	v_exp_f32_e32 v125, v125
	v_exp_f32_e32 v126, v126
	v_exp_f32_e32 v127, v127
	v_exp_f32_e32 v120, v120
	v_exp_f32_e32 v121, v121
	v_exp_f32_e32 v122, v122
	v_exp_f32_e32 v123, v123
	v_pk_add_f32 v[124:125], v[124:125], s[74:75] op_sel_hi:[1,0]
	v_pk_add_f32 v[126:127], v[126:127], s[74:75] op_sel_hi:[1,0]
	v_pk_add_f32 v[120:121], v[120:121], s[74:75] op_sel_hi:[1,0]
	v_pk_add_f32 v[122:123], v[122:123], s[74:75] op_sel_hi:[1,0]
	v_rcp_f32_e32 v124, v124
	v_rcp_f32_e32 v125, v125
	v_rcp_f32_e32 v126, v126
	v_rcp_f32_e32 v127, v127
	v_rcp_f32_e32 v120, v120
	v_rcp_f32_e32 v121, v121
	v_rcp_f32_e32 v122, v122
	v_rcp_f32_e32 v123, v123
	v_lshlrev_b32_e32 v234, 16, v140
	v_and_b32_e32 v235, 0xffff0000, v140
	v_lshlrev_b32_e32 v236, 16, v141
	v_and_b32_e32 v237, 0xffff0000, v141
	v_lshlrev_b32_e32 v238, 16, v142
	v_and_b32_e32 v239, 0xffff0000, v142
	v_lshlrev_b32_e32 v240, 16, v143
	v_and_b32_e32 v241, 0xffff0000, v143
	v_lshlrev_b32_e32 v242, 16, v148
	v_and_b32_e32 v243, 0xffff0000, v148
	v_lshlrev_b32_e32 v244, 16, v149
	v_and_b32_e32 v245, 0xffff0000, v149
	v_lshlrev_b32_e32 v246, 16, v150
	v_and_b32_e32 v247, 0xffff0000, v150
	v_lshlrev_b32_e32 v248, 16, v151
	v_and_b32_e32 v249, 0xffff0000, v151
	v_pk_fma_f32 v[124:125], v[124:125], v[242:243], v[234:235]
	v_pk_fma_f32 v[126:127], v[126:127], v[244:245], v[236:237]
	v_pk_fma_f32 v[120:121], v[120:121], v[246:247], v[238:239]
	v_pk_fma_f32 v[122:123], v[122:123], v[248:249], v[240:241]
	v_cvt_pk_bf16_f32 v234, v124, v125
	v_cvt_pk_bf16_f32 v235, v126, v127
	v_cvt_pk_bf16_f32 v236, v120, v121
	v_cvt_pk_bf16_f32 v237, v122, v123
	global_store_dwordx4 v183, v[234:237], s[40:41] offset:256
	v_cvt_pk_fp8_f32 v242, v124, v125
	v_cvt_pk_fp8_f32 v243, v120, v121
	v_cvt_pk_fp8_f32 v242, v126, v127 op_sel:[0,0,1]
	v_cvt_pk_fp8_f32 v243, v122, v123 op_sel:[0,0,1]
	v_pk_mul_f32 v[248:249], v[124:125], v[124:125]
	v_pk_fma_f32 v[248:249], v[126:127], v[126:127], v[248:249]
	v_pk_fma_f32 v[248:249], v[120:121], v[120:121], v[248:249]
	v_pk_fma_f32 v[248:249], v[122:123], v[122:123], v[248:249]
	global_store_dwordx2 v185, v[242:243], s[44:45] offset:128
	v_add_f32_e32 v0, v248, v249
	v_add_f32_e32 v250, v195, v0
	s_add_u32 s4, s8, 0x40000
	s_addc_u32 s5, s9, 0
	s_add_u32 s24, s22, 0x10000
	s_addc_u32 s25, s23, 0
	global_load_dwordx4 v[136:139], v183, s[4:5]
	global_load_dwordx4 v[144:147], v184, s[24:25]
	s_add_u32 s24, s24, 0x2000
	s_addc_u32 s25, s25, 0
	global_load_dwordx4 v[140:143], v183, s[4:5] offset:256
	global_load_dwordx4 v[148:151], v184, s[24:25]
	s_add_u32 s4, s8, 0x48000
	s_addc_u32 s5, s9, 0
	s_add_u32 s24, s22, 0x14000
	s_addc_u32 s25, s23, 0
	global_load_dwordx4 v[132:135], v183, s[4:5]
	global_load_dwordx4 v[124:127], v184, s[24:25]
	s_add_u32 s24, s24, 0x2000
	s_addc_u32 s25, s25, 0
	global_load_dwordx4 v[128:131], v183, s[4:5] offset:256
	global_load_dwordx4 v[120:123], v184, s[24:25]
	s_waitcnt vmcnt(20)
; __device__ __forceinline__ float sigmoidf_(float v) { return __builtin_amdgcn_rcpf(1.0f + __expf(-v)); }
; __device__ __forceinline__ u32x4 pack8(const f32x4 a, const f32x4 b) { u32x4 w; w.x = cvt_pk_bf16(a[0], a[1]); w.y = cvt_pk_bf16(a[2], a[3]); w.z = cvt_pk_bf16(b[0], b[1]); w.w = cvt_pk_bf16(b[2], b[3]); return w; }
; __device__ __forceinline__ void unpack8(const u32x4 w, f32x4& a, f32x4& b) { a[0] = bf_lo(w.x); a[1] = bf_hi(w.x); a[2] = bf_lo(w.y); a[3] = bf_hi(w.y); b[0] = bf_lo(w.z); b[1] = bf_hi(w.z); b[2] = bf_lo(w.w); b[3] = bf_hi(w.w); }
; __device__ __forceinline__ unsigned pack4_fp8(float a, float b, float c, float d) { unsigned w = 0u; w = __builtin_amdgcn_cvt_pk_fp8_f32(a, b, w, false); w = __builtin_amdgcn_cvt_pk_fp8_f32(c, d, w, true); return w; }
;     template <int KIND> __device__ __forceinline__ void run(f32x4 (&acc)[2][2][4][2], const Unit& u, int tid_in) const {
;     ...
;                     for (int ml = 0; ml < 2; ++ml) { const int m = mh * 2 + ml; int row = rbase + ai * 128 + m * 16; asm volatile("" : "+v"(row)); float ss = 0.f; const float r = rs[ai * 4 + m];
; #pragma unroll
;                         for (int bj = 0; bj < 2; ++bj) { const size_t off = (size_t)row * 1024 + u.pn * 256 + bj * 128 + cl; f32x4 a = acc[ai][bj][m][0], b = acc[ai][bj][m][1], p0, p1, x0, x1;
;                             unpack8(pv[ml][bj], p0, p1); unpack8(xv[ml][bj], x0, x1);
; #pragma unroll
;                             for (int j = 0; j < 4; ++j) { a[j] = sigmoidf_(a[j] * r) * p0[j]; b[j] = sigmoidf_(b[j] * r) * p1[j]; }
;                             const f32x4 o0 = x0 + a, o1 = x1 + b;
;                             *(u32x4*)(xb0 + off) = pack8(o0, o1);
;                             { u32x2 w8; w8.x = pack4_fp8(o0[0], o0[1], o0[2], o0[3]); w8.y = pack4_fp8(o1[0], o1[1], o1[2], o1[3]); *(u32x2*)((unsigned char*)zb + (size_t)row * (ZW * 2) + u.pn * 256 + bj * 128 + cl) = w8; }
;                             ss += (o0[0] * o0[0] + o0[1] * o0[1]) + (o0[2] * o0[2] + o0[3] * o0[3]) + (o1[0] * o1[0] + o1[1] * o1[1]) + (o1[2] * o1[2] + o1[3] * o1[3]); }
;                         ss += __shfl_xor(ss, 16); ss += __shfl_xor(ss, 32);
;                         if (fq == 0) ssq0[((size_t)u.pn * T_TOK + row) * 4 + wc] = ss; }
	v_mov_b32_e32 v226, v251
	s_add_u32 s40, s12, 0x8000
	s_addc_u32 s41, s13, 0
	s_add_u32 s44, s10, 0x16000
	s_addc_u32 s45, s11, 0
	v_pk_mul_f32 v[116:117], v[116:117], v[226:227] op_sel_hi:[1,0]
	v_pk_mul_f32 v[118:119], v[118:119], v[226:227] op_sel_hi:[1,0]
	v_pk_mul_f32 v[112:113], v[112:113], v[226:227] op_sel_hi:[1,0]
	v_pk_mul_f32 v[114:115], v[114:115], v[226:227] op_sel_hi:[1,0]
	v_pk_mul_f32 v[116:117], v[116:117], s[2:3] op_sel_hi:[1,0]
	v_pk_mul_f32 v[118:119], v[118:119], s[2:3] op_sel_hi:[1,0]
	v_pk_mul_f32 v[112:113], v[112:113], s[2:3] op_sel_hi:[1,0]
	v_pk_mul_f32 v[114:115], v[114:115], s[2:3] op_sel_hi:[1,0]
	v_exp_f32_e32 v116, v116
	v_exp_f32_e32 v117, v117
	v_exp_f32_e32 v118, v118
	v_exp_f32_e32 v119, v119
	v_exp_f32_e32 v112, v112
	v_exp_f32_e32 v113, v113
	v_exp_f32_e32 v114, v114
	v_exp_f32_e32 v115, v115
	v_pk_add_f32 v[116:117], v[116:117], s[74:75] op_sel_hi:[1,0]
	v_pk_add_f32 v[118:119], v[118:119], s[74:75] op_sel_hi:[1,0]
	v_pk_add_f32 v[112:113], v[112:113], s[74:75] op_sel_hi:[1,0]
	v_pk_add_f32 v[114:115], v[114:115], s[74:75] op_sel_hi:[1,0]
	v_rcp_f32_e32 v116, v116
	v_rcp_f32_e32 v117, v117
	v_rcp_f32_e32 v118, v118
	v_rcp_f32_e32 v119, v119
	v_rcp_f32_e32 v112, v112
	v_rcp_f32_e32 v113, v113
	v_rcp_f32_e32 v114, v114
	v_rcp_f32_e32 v115, v115
	v_lshlrev_b32_e32 v234, 16, v152
	v_and_b32_e32 v235, 0xffff0000, v152
	v_lshlrev_b32_e32 v236, 16, v153
	v_and_b32_e32 v237, 0xffff0000, v153
	v_lshlrev_b32_e32 v238, 16, v154
	v_and_b32_e32 v239, 0xffff0000, v154
	v_lshlrev_b32_e32 v240, 16, v155
	v_and_b32_e32 v241, 0xffff0000, v155
	v_lshlrev_b32_e32 v242, 16, v164
	v_and_b32_e32 v243, 0xffff0000, v164
	v_lshlrev_b32_e32 v244, 16, v165
	v_and_b32_e32 v245, 0xffff0000, v165
	v_lshlrev_b32_e32 v246, 16, v166
	v_and_b32_e32 v247, 0xffff0000, v166
	v_lshlrev_b32_e32 v248, 16, v167
	v_and_b32_e32 v249, 0xffff0000, v167
	v_pk_fma_f32 v[116:117], v[116:117], v[242:243], v[234:235]
	v_pk_fma_f32 v[118:119], v[118:119], v[244:245], v[236:237]
	v_pk_fma_f32 v[112:113], v[112:113], v[246:247], v[238:239]
	v_pk_fma_f32 v[114:115], v[114:115], v[248:249], v[240:241]
	v_cvt_pk_bf16_f32 v234, v116, v117
	v_cvt_pk_bf16_f32 v235, v118, v119
	v_cvt_pk_bf16_f32 v236, v112, v113
	v_cvt_pk_bf16_f32 v237, v114, v115
	global_store_dwordx4 v183, v[234:237], s[40:41]
	v_cvt_pk_fp8_f32 v242, v116, v117
	v_cvt_pk_fp8_f32 v243, v112, v113
	v_cvt_pk_fp8_f32 v242, v118, v119 op_sel:[0,0,1]
	v_cvt_pk_fp8_f32 v243, v114, v115 op_sel:[0,0,1]
	v_pk_mul_f32 v[248:249], v[116:117], v[116:117]
	v_pk_fma_f32 v[248:249], v[118:119], v[118:119], v[248:249]
	v_pk_fma_f32 v[248:249], v[112:113], v[112:113], v[248:249]
	v_pk_fma_f32 v[248:249], v[114:115], v[114:115], v[248:249]
	global_store_dwordx2 v185, v[242:243], s[44:45]
	v_add_f32_e32 v195, v248, v249
	v_pk_mul_f32 v[108:109], v[108:109], v[226:227] op_sel_hi:[1,0]
	v_pk_mul_f32 v[110:111], v[110:111], v[226:227] op_sel_hi:[1,0]
	v_pk_mul_f32 v[104:105], v[104:105], v[226:227] op_sel_hi:[1,0]
	v_pk_mul_f32 v[106:107], v[106:107], v[226:227] op_sel_hi:[1,0]
	v_pk_mul_f32 v[108:109], v[108:109], s[2:3] op_sel_hi:[1,0]
	v_pk_mul_f32 v[110:111], v[110:111], s[2:3] op_sel_hi:[1,0]
	v_pk_mul_f32 v[104:105], v[104:105], s[2:3] op_sel_hi:[1,0]
	v_pk_mul_f32 v[106:107], v[106:107], s[2:3] op_sel_hi:[1,0]
	v_exp_f32_e32 v108, v108
	v_exp_f32_e32 v109, v109
	v_exp_f32_e32 v110, v110
	v_exp_f32_e32 v111, v111
	v_exp_f32_e32 v104, v104
	v_exp_f32_e32 v105, v105
	v_exp_f32_e32 v106, v106
	v_exp_f32_e32 v107, v107
	v_pk_add_f32 v[108:109], v[108:109], s[74:75] op_sel_hi:[1,0]
	v_pk_add_f32 v[110:111], v[110:111], s[74:75] op_sel_hi:[1,0]
	v_pk_add_f32 v[104:105], v[104:105], s[74:75] op_sel_hi:[1,0]
	v_pk_add_f32 v[106:107], v[106:107], s[74:75] op_sel_hi:[1,0]
	v_rcp_f32_e32 v108, v108
	v_rcp_f32_e32 v109, v109
	v_rcp_f32_e32 v110, v110
	v_rcp_f32_e32 v111, v111
	v_rcp_f32_e32 v104, v104
	v_rcp_f32_e32 v105, v105
	v_rcp_f32_e32 v106, v106
	v_rcp_f32_e32 v107, v107
	v_lshlrev_b32_e32 v234, 16, v160
	v_and_b32_e32 v235, 0xffff0000, v160
	v_lshlrev_b32_e32 v236, 16, v161
	v_and_b32_e32 v237, 0xffff0000, v161
	v_lshlrev_b32_e32 v238, 16, v162
	v_and_b32_e32 v239, 0xffff0000, v162
	v_lshlrev_b32_e32 v240, 16, v163
	v_and_b32_e32 v241, 0xffff0000, v163
	v_lshlrev_b32_e32 v242, 16, v172
	v_and_b32_e32 v243, 0xffff0000, v172
	v_lshlrev_b32_e32 v244, 16, v173
	v_and_b32_e32 v245, 0xffff0000, v173
	v_lshlrev_b32_e32 v246, 16, v174
	v_and_b32_e32 v247, 0xffff0000, v174
	v_lshlrev_b32_e32 v248, 16, v175
	v_and_b32_e32 v249, 0xffff0000, v175
	v_pk_fma_f32 v[108:109], v[108:109], v[242:243], v[234:235]
	v_pk_fma_f32 v[110:111], v[110:111], v[244:245], v[236:237]
	v_pk_fma_f32 v[104:105], v[104:105], v[246:247], v[238:239]
	v_pk_fma_f32 v[106:107], v[106:107], v[248:249], v[240:241]
	v_cvt_pk_bf16_f32 v234, v108, v109
	v_cvt_pk_bf16_f32 v235, v110, v111
	v_cvt_pk_bf16_f32 v236, v104, v105
	v_cvt_pk_bf16_f32 v237, v106, v107
	global_store_dwordx4 v183, v[234:237], s[40:41] offset:256
	v_cvt_pk_fp8_f32 v242, v108, v109
	v_cvt_pk_fp8_f32 v243, v104, v105
	v_cvt_pk_fp8_f32 v242, v110, v111 op_sel:[0,0,1]
	v_cvt_pk_fp8_f32 v243, v106, v107 op_sel:[0,0,1]
	v_pk_mul_f32 v[248:249], v[108:109], v[108:109]
	v_pk_fma_f32 v[248:249], v[110:111], v[110:111], v[248:249]
	v_pk_fma_f32 v[248:249], v[104:105], v[104:105], v[248:249]
	v_pk_fma_f32 v[248:249], v[106:107], v[106:107], v[248:249]
	global_store_dwordx2 v185, v[242:243], s[44:45] offset:128
	v_add_f32_e32 v0, v248, v249
	v_add_f32_e32 v251, v195, v0
	s_add_u32 s4, s8, 0x50000
	s_addc_u32 s5, s9, 0
	s_add_u32 s24, s22, 0x18000
	s_addc_u32 s25, s23, 0
	global_load_dwordx4 v[152:155], v183, s[4:5]
	global_load_dwordx4 v[164:167], v184, s[24:25]
	s_add_u32 s24, s24, 0x2000
	s_addc_u32 s25, s25, 0
	global_load_dwordx4 v[160:163], v183, s[4:5] offset:256
	global_load_dwordx4 v[172:175], v184, s[24:25]
	s_add_u32 s4, s8, 0x58000
	s_addc_u32 s5, s9, 0
	s_add_u32 s24, s22, 0x1c000
	s_addc_u32 s25, s23, 0
	global_load_dwordx4 v[116:119], v183, s[4:5]
	global_load_dwordx4 v[108:111], v184, s[24:25]
	s_add_u32 s24, s24, 0x2000
	s_addc_u32 s25, s25, 0
	global_load_dwordx4 v[112:115], v183, s[4:5] offset:256
	global_load_dwordx4 v[104:107], v184, s[24:25]
	s_waitcnt vmcnt(28)
; __device__ __forceinline__ float sigmoidf_(float v) { return __builtin_amdgcn_rcpf(1.0f + __expf(-v)); }
; __device__ __forceinline__ u32x4 pack8(const f32x4 a, const f32x4 b) { u32x4 w; w.x = cvt_pk_bf16(a[0], a[1]); w.y = cvt_pk_bf16(a[2], a[3]); w.z = cvt_pk_bf16(b[0], b[1]); w.w = cvt_pk_bf16(b[2], b[3]); return w; }
; __device__ __forceinline__ void unpack8(const u32x4 w, f32x4& a, f32x4& b) { a[0] = bf_lo(w.x); a[1] = bf_hi(w.x); a[2] = bf_lo(w.y); a[3] = bf_hi(w.y); b[0] = bf_lo(w.z); b[1] = bf_hi(w.z); b[2] = bf_lo(w.w); b[3] = bf_hi(w.w); }
; __device__ __forceinline__ unsigned pack4_fp8(float a, float b, float c, float d) { unsigned w = 0u; w = __builtin_amdgcn_cvt_pk_fp8_f32(a, b, w, false); w = __builtin_amdgcn_cvt_pk_fp8_f32(c, d, w, true); return w; }
;     template <int KIND> __device__ __forceinline__ void run(f32x4 (&acc)[2][2][4][2], const Unit& u, int tid_in) const {
;     ...
;                     for (int ml = 0; ml < 2; ++ml) { const int m = mh * 2 + ml; int row = rbase + ai * 128 + m * 16; asm volatile("" : "+v"(row)); float ss = 0.f; const float r = rs[ai * 4 + m];
; #pragma unroll
;                         for (int bj = 0; bj < 2; ++bj) { const size_t off = (size_t)row * 1024 + u.pn * 256 + bj * 128 + cl; f32x4 a = acc[ai][bj][m][0], b = acc[ai][bj][m][1], p0, p1, x0, x1;
;                             unpack8(pv[ml][bj], p0, p1); unpack8(xv[ml][bj], x0, x1);
; #pragma unroll
;                             for (int j = 0; j < 4; ++j) { a[j] = sigmoidf_(a[j] * r) * p0[j]; b[j] = sigmoidf_(b[j] * r) * p1[j]; }
;                             const f32x4 o0 = x0 + a, o1 = x1 + b;
;                             *(u32x4*)(xb0 + off) = pack8(o0, o1);
;                             { u32x2 w8; w8.x = pack4_fp8(o0[0], o0[1], o0[2], o0[3]); w8.y = pack4_fp8(o1[0], o1[1], o1[2], o1[3]); *(u32x2*)((unsigned char*)zb + (size_t)row * (ZW * 2) + u.pn * 256 + bj * 128 + cl) = w8; }
;                             ss += (o0[0] * o0[0] + o0[1] * o0[1]) + (o0[2] * o0[2] + o0[3] * o0[3]) + (o1[0] * o1[0] + o1[1] * o1[1]) + (o1[2] * o1[2] + o1[3] * o1[3]); }
;                         ss += __shfl_xor(ss, 16); ss += __shfl_xor(ss, 32);
;                         if (fq == 0) ssq0[((size_t)u.pn * T_TOK + row) * 4 + wc] = ss; }
	v_mov_b32_e32 v226, v252
	s_add_u32 s40, s12, 0x10000
	s_addc_u32 s41, s13, 0
	s_add_u32 s44, s10, 0x2c000
	s_addc_u32 s45, s11, 0
	v_pk_mul_f32 v[100:101], v[100:101], v[226:227] op_sel_hi:[1,0]
	v_pk_mul_f32 v[102:103], v[102:103], v[226:227] op_sel_hi:[1,0]
	v_pk_mul_f32 v[96:97], v[96:97], v[226:227] op_sel_hi:[1,0]
	v_pk_mul_f32 v[98:99], v[98:99], v[226:227] op_sel_hi:[1,0]
	v_pk_mul_f32 v[100:101], v[100:101], s[2:3] op_sel_hi:[1,0]
	v_pk_mul_f32 v[102:103], v[102:103], s[2:3] op_sel_hi:[1,0]
	v_pk_mul_f32 v[96:97], v[96:97], s[2:3] op_sel_hi:[1,0]
	v_pk_mul_f32 v[98:99], v[98:99], s[2:3] op_sel_hi:[1,0]
	v_exp_f32_e32 v100, v100
	v_exp_f32_e32 v101, v101
	v_exp_f32_e32 v102, v102
	v_exp_f32_e32 v103, v103
	v_exp_f32_e32 v96, v96
	v_exp_f32_e32 v97, v97
	v_exp_f32_e32 v98, v98
	v_exp_f32_e32 v99, v99
	v_pk_add_f32 v[100:101], v[100:101], s[74:75] op_sel_hi:[1,0]
	v_pk_add_f32 v[102:103], v[102:103], s[74:75] op_sel_hi:[1,0]
	v_pk_add_f32 v[96:97], v[96:97], s[74:75] op_sel_hi:[1,0]
	v_pk_add_f32 v[98:99], v[98:99], s[74:75] op_sel_hi:[1,0]
	v_rcp_f32_e32 v100, v100
	v_rcp_f32_e32 v101, v101
	v_rcp_f32_e32 v102, v102
	v_rcp_f32_e32 v103, v103
	v_rcp_f32_e32 v96, v96
	v_rcp_f32_e32 v97, v97
	v_rcp_f32_e32 v98, v98
	v_rcp_f32_e32 v99, v99
	v_lshlrev_b32_e32 v234, 16, v176
	v_and_b32_e32 v235, 0xffff0000, v176
	v_lshlrev_b32_e32 v236, 16, v177
	v_and_b32_e32 v237, 0xffff0000, v177
	v_lshlrev_b32_e32 v238, 16, v178
	v_and_b32_e32 v239, 0xffff0000, v178
	v_lshlrev_b32_e32 v240, 16, v179
	v_and_b32_e32 v241, 0xffff0000, v179
	v_lshlrev_b32_e32 v242, 16, v200
	v_and_b32_e32 v243, 0xffff0000, v200
	v_lshlrev_b32_e32 v244, 16, v201
	v_and_b32_e32 v245, 0xffff0000, v201
	v_lshlrev_b32_e32 v246, 16, v202
	v_and_b32_e32 v247, 0xffff0000, v202
	v_lshlrev_b32_e32 v248, 16, v203
	v_and_b32_e32 v249, 0xffff0000, v203
	v_pk_fma_f32 v[100:101], v[100:101], v[242:243], v[234:235]
	v_pk_fma_f32 v[102:103], v[102:103], v[244:245], v[236:237]
	v_pk_fma_f32 v[96:97], v[96:97], v[246:247], v[238:239]
	v_pk_fma_f32 v[98:99], v[98:99], v[248:249], v[240:241]
	v_cvt_pk_bf16_f32 v234, v100, v101
	v_cvt_pk_bf16_f32 v235, v102, v103
	v_cvt_pk_bf16_f32 v236, v96, v97
	v_cvt_pk_bf16_f32 v237, v98, v99
	global_store_dwordx4 v183, v[234:237], s[40:41]
	v_cvt_pk_fp8_f32 v242, v100, v101
	v_cvt_pk_fp8_f32 v243, v96, v97
	v_cvt_pk_fp8_f32 v242, v102, v103 op_sel:[0,0,1]
	v_cvt_pk_fp8_f32 v243, v98, v99 op_sel:[0,0,1]
	v_pk_mul_f32 v[248:249], v[100:101], v[100:101]
	v_pk_fma_f32 v[248:249], v[102:103], v[102:103], v[248:249]
	v_pk_fma_f32 v[248:249], v[96:97], v[96:97], v[248:249]
	v_pk_fma_f32 v[248:249], v[98:99], v[98:99], v[248:249]
	global_store_dwordx2 v185, v[242:243], s[44:45]
	v_add_f32_e32 v195, v248, v249
	v_pk_mul_f32 v[92:93], v[92:93], v[226:227] op_sel_hi:[1,0]
	v_pk_mul_f32 v[94:95], v[94:95], v[226:227] op_sel_hi:[1,0]
	v_pk_mul_f32 v[88:89], v[88:89], v[226:227] op_sel_hi:[1,0]
	v_pk_mul_f32 v[90:91], v[90:91], v[226:227] op_sel_hi:[1,0]
	v_pk_mul_f32 v[92:93], v[92:93], s[2:3] op_sel_hi:[1,0]
	v_pk_mul_f32 v[94:95], v[94:95], s[2:3] op_sel_hi:[1,0]
	v_pk_mul_f32 v[88:89], v[88:89], s[2:3] op_sel_hi:[1,0]
	v_pk_mul_f32 v[90:91], v[90:91], s[2:3] op_sel_hi:[1,0]
	v_exp_f32_e32 v92, v92
	v_exp_f32_e32 v93, v93
	v_exp_f32_e32 v94, v94
	v_exp_f32_e32 v95, v95
	v_exp_f32_e32 v88, v88
	v_exp_f32_e32 v89, v89
	v_exp_f32_e32 v90, v90
	v_exp_f32_e32 v91, v91
	v_pk_add_f32 v[92:93], v[92:93], s[74:75] op_sel_hi:[1,0]
	v_pk_add_f32 v[94:95], v[94:95], s[74:75] op_sel_hi:[1,0]
	v_pk_add_f32 v[88:89], v[88:89], s[74:75] op_sel_hi:[1,0]
	v_pk_add_f32 v[90:91], v[90:91], s[74:75] op_sel_hi:[1,0]
	v_rcp_f32_e32 v92, v92
	v_rcp_f32_e32 v93, v93
	v_rcp_f32_e32 v94, v94
	v_rcp_f32_e32 v95, v95
	v_rcp_f32_e32 v88, v88
	v_rcp_f32_e32 v89, v89
	v_rcp_f32_e32 v90, v90
	v_rcp_f32_e32 v91, v91
	v_lshlrev_b32_e32 v234, 16, v196
	v_and_b32_e32 v235, 0xffff0000, v196
	v_lshlrev_b32_e32 v236, 16, v197
	v_and_b32_e32 v237, 0xffff0000, v197
	v_lshlrev_b32_e32 v238, 16, v198
	v_and_b32_e32 v239, 0xffff0000, v198
	v_lshlrev_b32_e32 v240, 16, v199
	v_and_b32_e32 v241, 0xffff0000, v199
	v_lshlrev_b32_e32 v242, 16, v204
	v_and_b32_e32 v243, 0xffff0000, v204
	v_lshlrev_b32_e32 v244, 16, v205
	v_and_b32_e32 v245, 0xffff0000, v205
	v_lshlrev_b32_e32 v246, 16, v206
	v_and_b32_e32 v247, 0xffff0000, v206
	v_lshlrev_b32_e32 v248, 16, v207
	v_and_b32_e32 v249, 0xffff0000, v207
	v_pk_fma_f32 v[92:93], v[92:93], v[242:243], v[234:235]
	v_pk_fma_f32 v[94:95], v[94:95], v[244:245], v[236:237]
	v_pk_fma_f32 v[88:89], v[88:89], v[246:247], v[238:239]
	v_pk_fma_f32 v[90:91], v[90:91], v[248:249], v[240:241]
	v_cvt_pk_bf16_f32 v234, v92, v93
	v_cvt_pk_bf16_f32 v235, v94, v95
	v_cvt_pk_bf16_f32 v236, v88, v89
	v_cvt_pk_bf16_f32 v237, v90, v91
	global_store_dwordx4 v183, v[234:237], s[40:41] offset:256
	v_cvt_pk_fp8_f32 v242, v92, v93
	v_cvt_pk_fp8_f32 v243, v88, v89
	v_cvt_pk_fp8_f32 v242, v94, v95 op_sel:[0,0,1]
	v_cvt_pk_fp8_f32 v243, v90, v91 op_sel:[0,0,1]
	v_pk_mul_f32 v[248:249], v[92:93], v[92:93]
	v_pk_fma_f32 v[248:249], v[94:95], v[94:95], v[248:249]
	v_pk_fma_f32 v[248:249], v[88:89], v[88:89], v[248:249]
	v_pk_fma_f32 v[248:249], v[90:91], v[90:91], v[248:249]
	global_store_dwordx2 v185, v[242:243], s[44:45] offset:128
	v_add_f32_e32 v0, v248, v249
	v_add_f32_e32 v252, v195, v0
	s_waitcnt vmcnt(28)
; __device__ __forceinline__ float sigmoidf_(float v) { return __builtin_amdgcn_rcpf(1.0f + __expf(-v)); }
; __device__ __forceinline__ u32x4 pack8(const f32x4 a, const f32x4 b) { u32x4 w; w.x = cvt_pk_bf16(a[0], a[1]); w.y = cvt_pk_bf16(a[2], a[3]); w.z = cvt_pk_bf16(b[0], b[1]); w.w = cvt_pk_bf16(b[2], b[3]); return w; }
; __device__ __forceinline__ void unpack8(const u32x4 w, f32x4& a, f32x4& b) { a[0] = bf_lo(w.x); a[1] = bf_hi(w.x); a[2] = bf_lo(w.y); a[3] = bf_hi(w.y); b[0] = bf_lo(w.z); b[1] = bf_hi(w.z); b[2] = bf_lo(w.w); b[3] = bf_hi(w.w); }
; __device__ __forceinline__ unsigned pack4_fp8(float a, float b, float c, float d) { unsigned w = 0u; w = __builtin_amdgcn_cvt_pk_fp8_f32(a, b, w, false); w = __builtin_amdgcn_cvt_pk_fp8_f32(c, d, w, true); return w; }
;     template <int KIND> __device__ __forceinline__ void run(f32x4 (&acc)[2][2][4][2], const Unit& u, int tid_in) const {
;     ...
;                     for (int ml = 0; ml < 2; ++ml) { const int m = mh * 2 + ml; int row = rbase + ai * 128 + m * 16; asm volatile("" : "+v"(row)); float ss = 0.f; const float r = rs[ai * 4 + m];
; #pragma unroll
;                         for (int bj = 0; bj < 2; ++bj) { const size_t off = (size_t)row * 1024 + u.pn * 256 + bj * 128 + cl; f32x4 a = acc[ai][bj][m][0], b = acc[ai][bj][m][1], p0, p1, x0, x1;
;                             unpack8(pv[ml][bj], p0, p1); unpack8(xv[ml][bj], x0, x1);
; #pragma unroll
;                             for (int j = 0; j < 4; ++j) { a[j] = sigmoidf_(a[j] * r) * p0[j]; b[j] = sigmoidf_(b[j] * r) * p1[j]; }
;                             const f32x4 o0 = x0 + a, o1 = x1 + b;
;                             *(u32x4*)(xb0 + off) = pack8(o0, o1);
;                             { u32x2 w8; w8.x = pack4_fp8(o0[0], o0[1], o0[2], o0[3]); w8.y = pack4_fp8(o1[0], o1[1], o1[2], o1[3]); *(u32x2*)((unsigned char*)zb + (size_t)row * (ZW * 2) + u.pn * 256 + bj * 128 + cl) = w8; }
;                             ss += (o0[0] * o0[0] + o0[1] * o0[1]) + (o0[2] * o0[2] + o0[3] * o0[3]) + (o1[0] * o1[0] + o1[1] * o1[1]) + (o1[2] * o1[2] + o1[3] * o1[3]); }
;                         ss += __shfl_xor(ss, 16); ss += __shfl_xor(ss, 32);
;                         if (fq == 0) ssq0[((size_t)u.pn * T_TOK + row) * 4 + wc] = ss; }
	v_mov_b32_e32 v226, v253
	s_add_u32 s40, s12, 0x18000
	s_addc_u32 s41, s13, 0
	s_add_u32 s44, s10, 0x42000
	s_addc_u32 s45, s11, 0
	v_pk_mul_f32 v[84:85], v[84:85], v[226:227] op_sel_hi:[1,0]
	v_pk_mul_f32 v[86:87], v[86:87], v[226:227] op_sel_hi:[1,0]
	v_pk_mul_f32 v[80:81], v[80:81], v[226:227] op_sel_hi:[1,0]
	v_pk_mul_f32 v[82:83], v[82:83], v[226:227] op_sel_hi:[1,0]
	v_pk_mul_f32 v[84:85], v[84:85], s[2:3] op_sel_hi:[1,0]
	v_pk_mul_f32 v[86:87], v[86:87], s[2:3] op_sel_hi:[1,0]
	v_pk_mul_f32 v[80:81], v[80:81], s[2:3] op_sel_hi:[1,0]
	v_pk_mul_f32 v[82:83], v[82:83], s[2:3] op_sel_hi:[1,0]
	v_exp_f32_e32 v84, v84
	v_exp_f32_e32 v85, v85
	v_exp_f32_e32 v86, v86
	v_exp_f32_e32 v87, v87
	v_exp_f32_e32 v80, v80
	v_exp_f32_e32 v81, v81
	v_exp_f32_e32 v82, v82
	v_exp_f32_e32 v83, v83
	v_pk_add_f32 v[84:85], v[84:85], s[74:75] op_sel_hi:[1,0]
	v_pk_add_f32 v[86:87], v[86:87], s[74:75] op_sel_hi:[1,0]
	v_pk_add_f32 v[80:81], v[80:81], s[74:75] op_sel_hi:[1,0]
	v_pk_add_f32 v[82:83], v[82:83], s[74:75] op_sel_hi:[1,0]
	v_rcp_f32_e32 v84, v84
	v_rcp_f32_e32 v85, v85
	v_rcp_f32_e32 v86, v86
	v_rcp_f32_e32 v87, v87
	v_rcp_f32_e32 v80, v80
	v_rcp_f32_e32 v81, v81
	v_rcp_f32_e32 v82, v82
	v_rcp_f32_e32 v83, v83
	v_lshlrev_b32_e32 v234, 16, v208
	v_and_b32_e32 v235, 0xffff0000, v208
	v_lshlrev_b32_e32 v236, 16, v209
	v_and_b32_e32 v237, 0xffff0000, v209
	v_lshlrev_b32_e32 v238, 16, v210
	v_and_b32_e32 v239, 0xffff0000, v210
	v_lshlrev_b32_e32 v240, 16, v211
	v_and_b32_e32 v241, 0xffff0000, v211
	v_lshlrev_b32_e32 v242, 16, v216
	v_and_b32_e32 v243, 0xffff0000, v216
	v_lshlrev_b32_e32 v244, 16, v217
	v_and_b32_e32 v245, 0xffff0000, v217
	v_lshlrev_b32_e32 v246, 16, v218
	v_and_b32_e32 v247, 0xffff0000, v218
	v_lshlrev_b32_e32 v248, 16, v219
	v_and_b32_e32 v249, 0xffff0000, v219
	v_pk_fma_f32 v[84:85], v[84:85], v[242:243], v[234:235]
	v_pk_fma_f32 v[86:87], v[86:87], v[244:245], v[236:237]
	v_pk_fma_f32 v[80:81], v[80:81], v[246:247], v[238:239]
	v_pk_fma_f32 v[82:83], v[82:83], v[248:249], v[240:241]
	v_cvt_pk_bf16_f32 v234, v84, v85
	v_cvt_pk_bf16_f32 v235, v86, v87
	v_cvt_pk_bf16_f32 v236, v80, v81
	v_cvt_pk_bf16_f32 v237, v82, v83
	global_store_dwordx4 v183, v[234:237], s[40:41]
	v_cvt_pk_fp8_f32 v242, v84, v85
	v_cvt_pk_fp8_f32 v243, v80, v81
	v_cvt_pk_fp8_f32 v242, v86, v87 op_sel:[0,0,1]
	v_cvt_pk_fp8_f32 v243, v82, v83 op_sel:[0,0,1]
	v_pk_mul_f32 v[248:249], v[84:85], v[84:85]
	v_pk_fma_f32 v[248:249], v[86:87], v[86:87], v[248:249]
	v_pk_fma_f32 v[248:249], v[80:81], v[80:81], v[248:249]
	v_pk_fma_f32 v[248:249], v[82:83], v[82:83], v[248:249]
	global_store_dwordx2 v185, v[242:243], s[44:45]
	v_add_f32_e32 v195, v248, v249
	v_pk_mul_f32 v[76:77], v[76:77], v[226:227] op_sel_hi:[1,0]
	v_pk_mul_f32 v[78:79], v[78:79], v[226:227] op_sel_hi:[1,0]
	v_pk_mul_f32 v[72:73], v[72:73], v[226:227] op_sel_hi:[1,0]
	v_pk_mul_f32 v[74:75], v[74:75], v[226:227] op_sel_hi:[1,0]
	v_pk_mul_f32 v[76:77], v[76:77], s[2:3] op_sel_hi:[1,0]
	v_pk_mul_f32 v[78:79], v[78:79], s[2:3] op_sel_hi:[1,0]
	v_pk_mul_f32 v[72:73], v[72:73], s[2:3] op_sel_hi:[1,0]
	v_pk_mul_f32 v[74:75], v[74:75], s[2:3] op_sel_hi:[1,0]
	v_exp_f32_e32 v76, v76
	v_exp_f32_e32 v77, v77
	v_exp_f32_e32 v78, v78
	v_exp_f32_e32 v79, v79
	v_exp_f32_e32 v72, v72
	v_exp_f32_e32 v73, v73
	v_exp_f32_e32 v74, v74
	v_exp_f32_e32 v75, v75
	v_pk_add_f32 v[76:77], v[76:77], s[74:75] op_sel_hi:[1,0]
	v_pk_add_f32 v[78:79], v[78:79], s[74:75] op_sel_hi:[1,0]
	v_pk_add_f32 v[72:73], v[72:73], s[74:75] op_sel_hi:[1,0]
	v_pk_add_f32 v[74:75], v[74:75], s[74:75] op_sel_hi:[1,0]
	v_rcp_f32_e32 v76, v76
	v_rcp_f32_e32 v77, v77
	v_rcp_f32_e32 v78, v78
	v_rcp_f32_e32 v79, v79
	v_rcp_f32_e32 v72, v72
	v_rcp_f32_e32 v73, v73
	v_rcp_f32_e32 v74, v74
	v_rcp_f32_e32 v75, v75
	v_lshlrev_b32_e32 v234, 16, v212
	v_and_b32_e32 v235, 0xffff0000, v212
	v_lshlrev_b32_e32 v236, 16, v213
	v_and_b32_e32 v237, 0xffff0000, v213
	v_lshlrev_b32_e32 v238, 16, v214
	v_and_b32_e32 v239, 0xffff0000, v214
	v_lshlrev_b32_e32 v240, 16, v215
	v_and_b32_e32 v241, 0xffff0000, v215
	v_lshlrev_b32_e32 v242, 16, v220
	v_and_b32_e32 v243, 0xffff0000, v220
	v_lshlrev_b32_e32 v244, 16, v221
	v_and_b32_e32 v245, 0xffff0000, v221
	v_lshlrev_b32_e32 v246, 16, v222
	v_and_b32_e32 v247, 0xffff0000, v222
	v_lshlrev_b32_e32 v248, 16, v223
	v_and_b32_e32 v249, 0xffff0000, v223
	v_pk_fma_f32 v[76:77], v[76:77], v[242:243], v[234:235]
	v_pk_fma_f32 v[78:79], v[78:79], v[244:245], v[236:237]
	v_pk_fma_f32 v[72:73], v[72:73], v[246:247], v[238:239]
	v_pk_fma_f32 v[74:75], v[74:75], v[248:249], v[240:241]
	v_cvt_pk_bf16_f32 v234, v76, v77
	v_cvt_pk_bf16_f32 v235, v78, v79
	v_cvt_pk_bf16_f32 v236, v72, v73
	v_cvt_pk_bf16_f32 v237, v74, v75
	global_store_dwordx4 v183, v[234:237], s[40:41] offset:256
	v_cvt_pk_fp8_f32 v242, v76, v77
	v_cvt_pk_fp8_f32 v243, v72, v73
	v_cvt_pk_fp8_f32 v242, v78, v79 op_sel:[0,0,1]
	v_cvt_pk_fp8_f32 v243, v74, v75 op_sel:[0,0,1]
	v_pk_mul_f32 v[248:249], v[76:77], v[76:77]
	v_pk_fma_f32 v[248:249], v[78:79], v[78:79], v[248:249]
	v_pk_fma_f32 v[248:249], v[72:73], v[72:73], v[248:249]
	v_pk_fma_f32 v[248:249], v[74:75], v[74:75], v[248:249]
	global_store_dwordx2 v185, v[242:243], s[44:45] offset:128
	v_add_f32_e32 v0, v248, v249
	v_add_f32_e32 v253, v195, v0
	s_waitcnt vmcnt(24)
; __device__ __forceinline__ float sigmoidf_(float v) { return __builtin_amdgcn_rcpf(1.0f + __expf(-v)); }
; __device__ __forceinline__ u32x4 pack8(const f32x4 a, const f32x4 b) { u32x4 w; w.x = cvt_pk_bf16(a[0], a[1]); w.y = cvt_pk_bf16(a[2], a[3]); w.z = cvt_pk_bf16(b[0], b[1]); w.w = cvt_pk_bf16(b[2], b[3]); return w; }
; __device__ __forceinline__ void unpack8(const u32x4 w, f32x4& a, f32x4& b) { a[0] = bf_lo(w.x); a[1] = bf_hi(w.x); a[2] = bf_lo(w.y); a[3] = bf_hi(w.y); b[0] = bf_lo(w.z); b[1] = bf_hi(w.z); b[2] = bf_lo(w.w); b[3] = bf_hi(w.w); }
; __device__ __forceinline__ unsigned pack4_fp8(float a, float b, float c, float d) { unsigned w = 0u; w = __builtin_amdgcn_cvt_pk_fp8_f32(a, b, w, false); w = __builtin_amdgcn_cvt_pk_fp8_f32(c, d, w, true); return w; }
;     template <int KIND> __device__ __forceinline__ void run(f32x4 (&acc)[2][2][4][2], const Unit& u, int tid_in) const {
;     ...
;                     for (int ml = 0; ml < 2; ++ml) { const int m = mh * 2 + ml; int row = rbase + ai * 128 + m * 16; asm volatile("" : "+v"(row)); float ss = 0.f; const float r = rs[ai * 4 + m];
; #pragma unroll
;                         for (int bj = 0; bj < 2; ++bj) { const size_t off = (size_t)row * 1024 + u.pn * 256 + bj * 128 + cl; f32x4 a = acc[ai][bj][m][0], b = acc[ai][bj][m][1], p0, p1, x0, x1;
;                             unpack8(pv[ml][bj], p0, p1); unpack8(xv[ml][bj], x0, x1);
; #pragma unroll
;                             for (int j = 0; j < 4; ++j) { a[j] = sigmoidf_(a[j] * r) * p0[j]; b[j] = sigmoidf_(b[j] * r) * p1[j]; }
;                             const f32x4 o0 = x0 + a, o1 = x1 + b;
;                             *(u32x4*)(xb0 + off) = pack8(o0, o1);
;                             { u32x2 w8; w8.x = pack4_fp8(o0[0], o0[1], o0[2], o0[3]); w8.y = pack4_fp8(o1[0], o1[1], o1[2], o1[3]); *(u32x2*)((unsigned char*)zb + (size_t)row * (ZW * 2) + u.pn * 256 + bj * 128 + cl) = w8; }
;                             ss += (o0[0] * o0[0] + o0[1] * o0[1]) + (o0[2] * o0[2] + o0[3] * o0[3]) + (o1[0] * o1[0] + o1[1] * o1[1]) + (o1[2] * o1[2] + o1[3] * o1[3]); }
;                         ss += __shfl_xor(ss, 16); ss += __shfl_xor(ss, 32);
;                         if (fq == 0) ssq0[((size_t)u.pn * T_TOK + row) * 4 + wc] = ss; }
	v_mov_b32_e32 v226, v254
	s_add_u32 s40, s12, 0x40000
	s_addc_u32 s41, s13, 0
	s_add_u32 s44, s10, 0xb0000
	s_addc_u32 s45, s11, 0
	v_pk_mul_f32 v[68:69], v[68:69], v[226:227] op_sel_hi:[1,0]
	v_pk_mul_f32 v[70:71], v[70:71], v[226:227] op_sel_hi:[1,0]
	v_pk_mul_f32 v[64:65], v[64:65], v[226:227] op_sel_hi:[1,0]
	v_pk_mul_f32 v[66:67], v[66:67], v[226:227] op_sel_hi:[1,0]
	v_pk_mul_f32 v[68:69], v[68:69], s[2:3] op_sel_hi:[1,0]
	v_pk_mul_f32 v[70:71], v[70:71], s[2:3] op_sel_hi:[1,0]
	v_pk_mul_f32 v[64:65], v[64:65], s[2:3] op_sel_hi:[1,0]
	v_pk_mul_f32 v[66:67], v[66:67], s[2:3] op_sel_hi:[1,0]
	v_exp_f32_e32 v68, v68
	v_exp_f32_e32 v69, v69
	v_exp_f32_e32 v70, v70
	v_exp_f32_e32 v71, v71
	v_exp_f32_e32 v64, v64
	v_exp_f32_e32 v65, v65
	v_exp_f32_e32 v66, v66
	v_exp_f32_e32 v67, v67
	v_pk_add_f32 v[68:69], v[68:69], s[74:75] op_sel_hi:[1,0]
	v_pk_add_f32 v[70:71], v[70:71], s[74:75] op_sel_hi:[1,0]
	v_pk_add_f32 v[64:65], v[64:65], s[74:75] op_sel_hi:[1,0]
	v_pk_add_f32 v[66:67], v[66:67], s[74:75] op_sel_hi:[1,0]
	v_rcp_f32_e32 v68, v68
	v_rcp_f32_e32 v69, v69
	v_rcp_f32_e32 v70, v70
	v_rcp_f32_e32 v71, v71
	v_rcp_f32_e32 v64, v64
	v_rcp_f32_e32 v65, v65
	v_rcp_f32_e32 v66, v66
	v_rcp_f32_e32 v67, v67
	v_lshlrev_b32_e32 v234, 16, v136
	v_and_b32_e32 v235, 0xffff0000, v136
	v_lshlrev_b32_e32 v236, 16, v137
	v_and_b32_e32 v237, 0xffff0000, v137
	v_lshlrev_b32_e32 v238, 16, v138
	v_and_b32_e32 v239, 0xffff0000, v138
	v_lshlrev_b32_e32 v240, 16, v139
	v_and_b32_e32 v241, 0xffff0000, v139
	v_lshlrev_b32_e32 v242, 16, v144
	v_and_b32_e32 v243, 0xffff0000, v144
	v_lshlrev_b32_e32 v244, 16, v145
	v_and_b32_e32 v245, 0xffff0000, v145
	v_lshlrev_b32_e32 v246, 16, v146
	v_and_b32_e32 v247, 0xffff0000, v146
	v_lshlrev_b32_e32 v248, 16, v147
	v_and_b32_e32 v249, 0xffff0000, v147
	v_pk_fma_f32 v[68:69], v[68:69], v[242:243], v[234:235]
	v_pk_fma_f32 v[70:71], v[70:71], v[244:245], v[236:237]
	v_pk_fma_f32 v[64:65], v[64:65], v[246:247], v[238:239]
	v_pk_fma_f32 v[66:67], v[66:67], v[248:249], v[240:241]
	v_cvt_pk_bf16_f32 v234, v68, v69
	v_cvt_pk_bf16_f32 v235, v70, v71
	v_cvt_pk_bf16_f32 v236, v64, v65
	v_cvt_pk_bf16_f32 v237, v66, v67
	global_store_dwordx4 v183, v[234:237], s[40:41]
	v_cvt_pk_fp8_f32 v242, v68, v69
	v_cvt_pk_fp8_f32 v243, v64, v65
	v_cvt_pk_fp8_f32 v242, v70, v71 op_sel:[0,0,1]
	v_cvt_pk_fp8_f32 v243, v66, v67 op_sel:[0,0,1]
	v_pk_mul_f32 v[248:249], v[68:69], v[68:69]
	v_pk_fma_f32 v[248:249], v[70:71], v[70:71], v[248:249]
	v_pk_fma_f32 v[248:249], v[64:65], v[64:65], v[248:249]
	v_pk_fma_f32 v[248:249], v[66:67], v[66:67], v[248:249]
	global_store_dwordx2 v185, v[242:243], s[44:45]
	v_add_f32_e32 v195, v248, v249
	v_pk_mul_f32 v[60:61], v[60:61], v[226:227] op_sel_hi:[1,0]
	v_pk_mul_f32 v[62:63], v[62:63], v[226:227] op_sel_hi:[1,0]
	v_pk_mul_f32 v[56:57], v[56:57], v[226:227] op_sel_hi:[1,0]
	v_pk_mul_f32 v[58:59], v[58:59], v[226:227] op_sel_hi:[1,0]
	v_pk_mul_f32 v[60:61], v[60:61], s[2:3] op_sel_hi:[1,0]
	v_pk_mul_f32 v[62:63], v[62:63], s[2:3] op_sel_hi:[1,0]
	v_pk_mul_f32 v[56:57], v[56:57], s[2:3] op_sel_hi:[1,0]
	v_pk_mul_f32 v[58:59], v[58:59], s[2:3] op_sel_hi:[1,0]
	v_exp_f32_e32 v60, v60
	v_exp_f32_e32 v61, v61
	v_exp_f32_e32 v62, v62
	v_exp_f32_e32 v63, v63
	v_exp_f32_e32 v56, v56
	v_exp_f32_e32 v57, v57
	v_exp_f32_e32 v58, v58
	v_exp_f32_e32 v59, v59
	v_pk_add_f32 v[60:61], v[60:61], s[74:75] op_sel_hi:[1,0]
	v_pk_add_f32 v[62:63], v[62:63], s[74:75] op_sel_hi:[1,0]
	v_pk_add_f32 v[56:57], v[56:57], s[74:75] op_sel_hi:[1,0]
	v_pk_add_f32 v[58:59], v[58:59], s[74:75] op_sel_hi:[1,0]
	v_rcp_f32_e32 v60, v60
	v_rcp_f32_e32 v61, v61
	v_rcp_f32_e32 v62, v62
	v_rcp_f32_e32 v63, v63
	v_rcp_f32_e32 v56, v56
	v_rcp_f32_e32 v57, v57
	v_rcp_f32_e32 v58, v58
	v_rcp_f32_e32 v59, v59
	v_lshlrev_b32_e32 v234, 16, v140
	v_and_b32_e32 v235, 0xffff0000, v140
	v_lshlrev_b32_e32 v236, 16, v141
	v_and_b32_e32 v237, 0xffff0000, v141
	v_lshlrev_b32_e32 v238, 16, v142
	v_and_b32_e32 v239, 0xffff0000, v142
	v_lshlrev_b32_e32 v240, 16, v143
	v_and_b32_e32 v241, 0xffff0000, v143
	v_lshlrev_b32_e32 v242, 16, v148
	v_and_b32_e32 v243, 0xffff0000, v148
	v_lshlrev_b32_e32 v244, 16, v149
	v_and_b32_e32 v245, 0xffff0000, v149
	v_lshlrev_b32_e32 v246, 16, v150
	v_and_b32_e32 v247, 0xffff0000, v150
	v_lshlrev_b32_e32 v248, 16, v151
	v_and_b32_e32 v249, 0xffff0000, v151
	v_pk_fma_f32 v[60:61], v[60:61], v[242:243], v[234:235]
	v_pk_fma_f32 v[62:63], v[62:63], v[244:245], v[236:237]
	v_pk_fma_f32 v[56:57], v[56:57], v[246:247], v[238:239]
	v_pk_fma_f32 v[58:59], v[58:59], v[248:249], v[240:241]
	v_cvt_pk_bf16_f32 v234, v60, v61
	v_cvt_pk_bf16_f32 v235, v62, v63
	v_cvt_pk_bf16_f32 v236, v56, v57
	v_cvt_pk_bf16_f32 v237, v58, v59
	global_store_dwordx4 v183, v[234:237], s[40:41] offset:256
	v_cvt_pk_fp8_f32 v242, v60, v61
	v_cvt_pk_fp8_f32 v243, v56, v57
	v_cvt_pk_fp8_f32 v242, v62, v63 op_sel:[0,0,1]
	v_cvt_pk_fp8_f32 v243, v58, v59 op_sel:[0,0,1]
	v_pk_mul_f32 v[248:249], v[60:61], v[60:61]
	v_pk_fma_f32 v[248:249], v[62:63], v[62:63], v[248:249]
	v_pk_fma_f32 v[248:249], v[56:57], v[56:57], v[248:249]
	v_pk_fma_f32 v[248:249], v[58:59], v[58:59], v[248:249]
	global_store_dwordx2 v185, v[242:243], s[44:45] offset:128
	v_add_f32_e32 v0, v248, v249
	v_add_f32_e32 v254, v195, v0
	s_waitcnt vmcnt(24)
; __device__ __forceinline__ float sigmoidf_(float v) { return __builtin_amdgcn_rcpf(1.0f + __expf(-v)); }
; __device__ __forceinline__ u32x4 pack8(const f32x4 a, const f32x4 b) { u32x4 w; w.x = cvt_pk_bf16(a[0], a[1]); w.y = cvt_pk_bf16(a[2], a[3]); w.z = cvt_pk_bf16(b[0], b[1]); w.w = cvt_pk_bf16(b[2], b[3]); return w; }
; __device__ __forceinline__ void unpack8(const u32x4 w, f32x4& a, f32x4& b) { a[0] = bf_lo(w.x); a[1] = bf_hi(w.x); a[2] = bf_lo(w.y); a[3] = bf_hi(w.y); b[0] = bf_lo(w.z); b[1] = bf_hi(w.z); b[2] = bf_lo(w.w); b[3] = bf_hi(w.w); }
; __device__ __forceinline__ unsigned pack4_fp8(float a, float b, float c, float d) { unsigned w = 0u; w = __builtin_amdgcn_cvt_pk_fp8_f32(a, b, w, false); w = __builtin_amdgcn_cvt_pk_fp8_f32(c, d, w, true); return w; }
;     template <int KIND> __device__ __forceinline__ void run(f32x4 (&acc)[2][2][4][2], const Unit& u, int tid_in) const {
;     ...
;                     for (int ml = 0; ml < 2; ++ml) { const int m = mh * 2 + ml; int row = rbase + ai * 128 + m * 16; asm volatile("" : "+v"(row)); float ss = 0.f; const float r = rs[ai * 4 + m];
; #pragma unroll
;                         for (int bj = 0; bj < 2; ++bj) { const size_t off = (size_t)row * 1024 + u.pn * 256 + bj * 128 + cl; f32x4 a = acc[ai][bj][m][0], b = acc[ai][bj][m][1], p0, p1, x0, x1;
;                             unpack8(pv[ml][bj], p0, p1); unpack8(xv[ml][bj], x0, x1);
; #pragma unroll
;                             for (int j = 0; j < 4; ++j) { a[j] = sigmoidf_(a[j] * r) * p0[j]; b[j] = sigmoidf_(b[j] * r) * p1[j]; }
;                             const f32x4 o0 = x0 + a, o1 = x1 + b;
;                             *(u32x4*)(xb0 + off) = pack8(o0, o1);
;                             { u32x2 w8; w8.x = pack4_fp8(o0[0], o0[1], o0[2], o0[3]); w8.y = pack4_fp8(o1[0], o1[1], o1[2], o1[3]); *(u32x2*)((unsigned char*)zb + (size_t)row * (ZW * 2) + u.pn * 256 + bj * 128 + cl) = w8; }
;                             ss += (o0[0] * o0[0] + o0[1] * o0[1]) + (o0[2] * o0[2] + o0[3] * o0[3]) + (o1[0] * o1[0] + o1[1] * o1[1]) + (o1[2] * o1[2] + o1[3] * o1[3]); }
;                         ss += __shfl_xor(ss, 16); ss += __shfl_xor(ss, 32);
;                         if (fq == 0) ssq0[((size_t)u.pn * T_TOK + row) * 4 + wc] = ss; }
	v_mov_b32_e32 v226, v255
	s_add_u32 s40, s12, 0x48000
	s_addc_u32 s41, s13, 0
	s_add_u32 s44, s10, 0xc6000
	s_addc_u32 s45, s11, 0
	v_pk_mul_f32 v[52:53], v[52:53], v[226:227] op_sel_hi:[1,0]
	v_pk_mul_f32 v[54:55], v[54:55], v[226:227] op_sel_hi:[1,0]
	v_pk_mul_f32 v[48:49], v[48:49], v[226:227] op_sel_hi:[1,0]
	v_pk_mul_f32 v[50:51], v[50:51], v[226:227] op_sel_hi:[1,0]
	v_pk_mul_f32 v[52:53], v[52:53], s[2:3] op_sel_hi:[1,0]
	v_pk_mul_f32 v[54:55], v[54:55], s[2:3] op_sel_hi:[1,0]
	v_pk_mul_f32 v[48:49], v[48:49], s[2:3] op_sel_hi:[1,0]
	v_pk_mul_f32 v[50:51], v[50:51], s[2:3] op_sel_hi:[1,0]
	v_exp_f32_e32 v52, v52
	v_exp_f32_e32 v53, v53
	v_exp_f32_e32 v54, v54
	v_exp_f32_e32 v55, v55
	v_exp_f32_e32 v48, v48
	v_exp_f32_e32 v49, v49
	v_exp_f32_e32 v50, v50
	v_exp_f32_e32 v51, v51
	v_pk_add_f32 v[52:53], v[52:53], s[74:75] op_sel_hi:[1,0]
	v_pk_add_f32 v[54:55], v[54:55], s[74:75] op_sel_hi:[1,0]
	v_pk_add_f32 v[48:49], v[48:49], s[74:75] op_sel_hi:[1,0]
	v_pk_add_f32 v[50:51], v[50:51], s[74:75] op_sel_hi:[1,0]
	v_rcp_f32_e32 v52, v52
	v_rcp_f32_e32 v53, v53
	v_rcp_f32_e32 v54, v54
	v_rcp_f32_e32 v55, v55
	v_rcp_f32_e32 v48, v48
	v_rcp_f32_e32 v49, v49
	v_rcp_f32_e32 v50, v50
	v_rcp_f32_e32 v51, v51
	v_lshlrev_b32_e32 v234, 16, v132
	v_and_b32_e32 v235, 0xffff0000, v132
	v_lshlrev_b32_e32 v236, 16, v133
	v_and_b32_e32 v237, 0xffff0000, v133
	v_lshlrev_b32_e32 v238, 16, v134
	v_and_b32_e32 v239, 0xffff0000, v134
	v_lshlrev_b32_e32 v240, 16, v135
	v_and_b32_e32 v241, 0xffff0000, v135
	v_lshlrev_b32_e32 v242, 16, v124
	v_and_b32_e32 v243, 0xffff0000, v124
	v_lshlrev_b32_e32 v244, 16, v125
	v_and_b32_e32 v245, 0xffff0000, v125
	v_lshlrev_b32_e32 v246, 16, v126
	v_and_b32_e32 v247, 0xffff0000, v126
	v_lshlrev_b32_e32 v248, 16, v127
	v_and_b32_e32 v249, 0xffff0000, v127
	v_pk_fma_f32 v[52:53], v[52:53], v[242:243], v[234:235]
	v_pk_fma_f32 v[54:55], v[54:55], v[244:245], v[236:237]
	v_pk_fma_f32 v[48:49], v[48:49], v[246:247], v[238:239]
	v_pk_fma_f32 v[50:51], v[50:51], v[248:249], v[240:241]
	v_cvt_pk_bf16_f32 v234, v52, v53
	v_cvt_pk_bf16_f32 v235, v54, v55
	v_cvt_pk_bf16_f32 v236, v48, v49
	v_cvt_pk_bf16_f32 v237, v50, v51
	global_store_dwordx4 v183, v[234:237], s[40:41]
	v_cvt_pk_fp8_f32 v242, v52, v53
	v_cvt_pk_fp8_f32 v243, v48, v49
	v_cvt_pk_fp8_f32 v242, v54, v55 op_sel:[0,0,1]
	v_cvt_pk_fp8_f32 v243, v50, v51 op_sel:[0,0,1]
	v_pk_mul_f32 v[248:249], v[52:53], v[52:53]
	v_pk_fma_f32 v[248:249], v[54:55], v[54:55], v[248:249]
	v_pk_fma_f32 v[248:249], v[48:49], v[48:49], v[248:249]
	v_pk_fma_f32 v[248:249], v[50:51], v[50:51], v[248:249]
	global_store_dwordx2 v185, v[242:243], s[44:45]
	v_add_f32_e32 v195, v248, v249
	v_pk_mul_f32 v[44:45], v[44:45], v[226:227] op_sel_hi:[1,0]
	v_pk_mul_f32 v[46:47], v[46:47], v[226:227] op_sel_hi:[1,0]
	v_pk_mul_f32 v[40:41], v[40:41], v[226:227] op_sel_hi:[1,0]
	v_pk_mul_f32 v[42:43], v[42:43], v[226:227] op_sel_hi:[1,0]
	v_pk_mul_f32 v[44:45], v[44:45], s[2:3] op_sel_hi:[1,0]
	v_pk_mul_f32 v[46:47], v[46:47], s[2:3] op_sel_hi:[1,0]
	v_pk_mul_f32 v[40:41], v[40:41], s[2:3] op_sel_hi:[1,0]
	v_pk_mul_f32 v[42:43], v[42:43], s[2:3] op_sel_hi:[1,0]
	v_exp_f32_e32 v44, v44
	v_exp_f32_e32 v45, v45
	v_exp_f32_e32 v46, v46
	v_exp_f32_e32 v47, v47
	v_exp_f32_e32 v40, v40
	v_exp_f32_e32 v41, v41
	v_exp_f32_e32 v42, v42
	v_exp_f32_e32 v43, v43
	v_pk_add_f32 v[44:45], v[44:45], s[74:75] op_sel_hi:[1,0]
	v_pk_add_f32 v[46:47], v[46:47], s[74:75] op_sel_hi:[1,0]
	v_pk_add_f32 v[40:41], v[40:41], s[74:75] op_sel_hi:[1,0]
	v_pk_add_f32 v[42:43], v[42:43], s[74:75] op_sel_hi:[1,0]
	v_rcp_f32_e32 v44, v44
	v_rcp_f32_e32 v45, v45
	v_rcp_f32_e32 v46, v46
	v_rcp_f32_e32 v47, v47
	v_rcp_f32_e32 v40, v40
	v_rcp_f32_e32 v41, v41
	v_rcp_f32_e32 v42, v42
	v_rcp_f32_e32 v43, v43
	v_lshlrev_b32_e32 v234, 16, v128
	v_and_b32_e32 v235, 0xffff0000, v128
	v_lshlrev_b32_e32 v236, 16, v129
	v_and_b32_e32 v237, 0xffff0000, v129
	v_lshlrev_b32_e32 v238, 16, v130
	v_and_b32_e32 v239, 0xffff0000, v130
	v_lshlrev_b32_e32 v240, 16, v131
	v_and_b32_e32 v241, 0xffff0000, v131
	v_lshlrev_b32_e32 v242, 16, v120
	v_and_b32_e32 v243, 0xffff0000, v120
	v_lshlrev_b32_e32 v244, 16, v121
	v_and_b32_e32 v245, 0xffff0000, v121
	v_lshlrev_b32_e32 v246, 16, v122
	v_and_b32_e32 v247, 0xffff0000, v122
	v_lshlrev_b32_e32 v248, 16, v123
	v_and_b32_e32 v249, 0xffff0000, v123
	v_pk_fma_f32 v[44:45], v[44:45], v[242:243], v[234:235]
	v_pk_fma_f32 v[46:47], v[46:47], v[244:245], v[236:237]
	v_pk_fma_f32 v[40:41], v[40:41], v[246:247], v[238:239]
	v_pk_fma_f32 v[42:43], v[42:43], v[248:249], v[240:241]
	v_cvt_pk_bf16_f32 v234, v44, v45
	v_cvt_pk_bf16_f32 v235, v46, v47
	v_cvt_pk_bf16_f32 v236, v40, v41
	v_cvt_pk_bf16_f32 v237, v42, v43
	global_store_dwordx4 v183, v[234:237], s[40:41] offset:256
	v_cvt_pk_fp8_f32 v242, v44, v45
	v_cvt_pk_fp8_f32 v243, v40, v41
	v_cvt_pk_fp8_f32 v242, v46, v47 op_sel:[0,0,1]
	v_cvt_pk_fp8_f32 v243, v42, v43 op_sel:[0,0,1]
	v_pk_mul_f32 v[248:249], v[44:45], v[44:45]
	v_pk_fma_f32 v[248:249], v[46:47], v[46:47], v[248:249]
	v_pk_fma_f32 v[248:249], v[40:41], v[40:41], v[248:249]
	v_pk_fma_f32 v[248:249], v[42:43], v[42:43], v[248:249]
	global_store_dwordx2 v185, v[242:243], s[44:45] offset:128
	v_add_f32_e32 v0, v248, v249
	v_add_f32_e32 v255, v195, v0
	s_waitcnt vmcnt(20)
; __device__ __forceinline__ float sigmoidf_(float v) { return __builtin_amdgcn_rcpf(1.0f + __expf(-v)); }
; __device__ __forceinline__ u32x4 pack8(const f32x4 a, const f32x4 b) { u32x4 w; w.x = cvt_pk_bf16(a[0], a[1]); w.y = cvt_pk_bf16(a[2], a[3]); w.z = cvt_pk_bf16(b[0], b[1]); w.w = cvt_pk_bf16(b[2], b[3]); return w; }
; __device__ __forceinline__ void unpack8(const u32x4 w, f32x4& a, f32x4& b) { a[0] = bf_lo(w.x); a[1] = bf_hi(w.x); a[2] = bf_lo(w.y); a[3] = bf_hi(w.y); b[0] = bf_lo(w.z); b[1] = bf_hi(w.z); b[2] = bf_lo(w.w); b[3] = bf_hi(w.w); }
; __device__ __forceinline__ unsigned pack4_fp8(float a, float b, float c, float d) { unsigned w = 0u; w = __builtin_amdgcn_cvt_pk_fp8_f32(a, b, w, false); w = __builtin_amdgcn_cvt_pk_fp8_f32(c, d, w, true); return w; }
;     template <int KIND> __device__ __forceinline__ void run(f32x4 (&acc)[2][2][4][2], const Unit& u, int tid_in) const {
;     ...
;                     for (int ml = 0; ml < 2; ++ml) { const int m = mh * 2 + ml; int row = rbase + ai * 128 + m * 16; asm volatile("" : "+v"(row)); float ss = 0.f; const float r = rs[ai * 4 + m];
; #pragma unroll
;                         for (int bj = 0; bj < 2; ++bj) { const size_t off = (size_t)row * 1024 + u.pn * 256 + bj * 128 + cl; f32x4 a = acc[ai][bj][m][0], b = acc[ai][bj][m][1], p0, p1, x0, x1;
;                             unpack8(pv[ml][bj], p0, p1); unpack8(xv[ml][bj], x0, x1);
; #pragma unroll
;                             for (int j = 0; j < 4; ++j) { a[j] = sigmoidf_(a[j] * r) * p0[j]; b[j] = sigmoidf_(b[j] * r) * p1[j]; }
;                             const f32x4 o0 = x0 + a, o1 = x1 + b;
;                             *(u32x4*)(xb0 + off) = pack8(o0, o1);
;                             { u32x2 w8; w8.x = pack4_fp8(o0[0], o0[1], o0[2], o0[3]); w8.y = pack4_fp8(o1[0], o1[1], o1[2], o1[3]); *(u32x2*)((unsigned char*)zb + (size_t)row * (ZW * 2) + u.pn * 256 + bj * 128 + cl) = w8; }
;                             ss += (o0[0] * o0[0] + o0[1] * o0[1]) + (o0[2] * o0[2] + o0[3] * o0[3]) + (o1[0] * o1[0] + o1[1] * o1[1]) + (o1[2] * o1[2] + o1[3] * o1[3]); }
;                         ss += __shfl_xor(ss, 16); ss += __shfl_xor(ss, 32);
;                         if (fq == 0) ssq0[((size_t)u.pn * T_TOK + row) * 4 + wc] = ss; }
	v_mov_b32_e32 v226, v224
	s_add_u32 s40, s12, 0x50000
	s_addc_u32 s41, s13, 0
	s_add_u32 s44, s10, 0xdc000
	s_addc_u32 s45, s11, 0
	v_pk_mul_f32 v[36:37], v[36:37], v[226:227] op_sel_hi:[1,0]
	v_pk_mul_f32 v[38:39], v[38:39], v[226:227] op_sel_hi:[1,0]
	v_pk_mul_f32 v[32:33], v[32:33], v[226:227] op_sel_hi:[1,0]
	v_pk_mul_f32 v[34:35], v[34:35], v[226:227] op_sel_hi:[1,0]
	v_pk_mul_f32 v[36:37], v[36:37], s[2:3] op_sel_hi:[1,0]
	v_pk_mul_f32 v[38:39], v[38:39], s[2:3] op_sel_hi:[1,0]
	v_pk_mul_f32 v[32:33], v[32:33], s[2:3] op_sel_hi:[1,0]
	v_pk_mul_f32 v[34:35], v[34:35], s[2:3] op_sel_hi:[1,0]
	v_exp_f32_e32 v36, v36
	v_exp_f32_e32 v37, v37
	v_exp_f32_e32 v38, v38
	v_exp_f32_e32 v39, v39
	v_exp_f32_e32 v32, v32
	v_exp_f32_e32 v33, v33
	v_exp_f32_e32 v34, v34
	v_exp_f32_e32 v35, v35
	v_pk_add_f32 v[36:37], v[36:37], s[74:75] op_sel_hi:[1,0]
	v_pk_add_f32 v[38:39], v[38:39], s[74:75] op_sel_hi:[1,0]
	v_pk_add_f32 v[32:33], v[32:33], s[74:75] op_sel_hi:[1,0]
	v_pk_add_f32 v[34:35], v[34:35], s[74:75] op_sel_hi:[1,0]
	v_rcp_f32_e32 v36, v36
	v_rcp_f32_e32 v37, v37
	v_rcp_f32_e32 v38, v38
	v_rcp_f32_e32 v39, v39
	v_rcp_f32_e32 v32, v32
	v_rcp_f32_e32 v33, v33
	v_rcp_f32_e32 v34, v34
	v_rcp_f32_e32 v35, v35
	v_lshlrev_b32_e32 v234, 16, v152
	v_and_b32_e32 v235, 0xffff0000, v152
	v_lshlrev_b32_e32 v236, 16, v153
	v_and_b32_e32 v237, 0xffff0000, v153
	v_lshlrev_b32_e32 v238, 16, v154
	v_and_b32_e32 v239, 0xffff0000, v154
	v_lshlrev_b32_e32 v240, 16, v155
	v_and_b32_e32 v241, 0xffff0000, v155
	v_lshlrev_b32_e32 v242, 16, v164
	v_and_b32_e32 v243, 0xffff0000, v164
	v_lshlrev_b32_e32 v244, 16, v165
	v_and_b32_e32 v245, 0xffff0000, v165
	v_lshlrev_b32_e32 v246, 16, v166
	v_and_b32_e32 v247, 0xffff0000, v166
	v_lshlrev_b32_e32 v248, 16, v167
	v_and_b32_e32 v249, 0xffff0000, v167
	v_pk_fma_f32 v[36:37], v[36:37], v[242:243], v[234:235]
	v_pk_fma_f32 v[38:39], v[38:39], v[244:245], v[236:237]
	v_pk_fma_f32 v[32:33], v[32:33], v[246:247], v[238:239]
	v_pk_fma_f32 v[34:35], v[34:35], v[248:249], v[240:241]
	v_cvt_pk_bf16_f32 v234, v36, v37
	v_cvt_pk_bf16_f32 v235, v38, v39
	v_cvt_pk_bf16_f32 v236, v32, v33
	v_cvt_pk_bf16_f32 v237, v34, v35
	global_store_dwordx4 v183, v[234:237], s[40:41]
	v_cvt_pk_fp8_f32 v242, v36, v37
	v_cvt_pk_fp8_f32 v243, v32, v33
	v_cvt_pk_fp8_f32 v242, v38, v39 op_sel:[0,0,1]
	v_cvt_pk_fp8_f32 v243, v34, v35 op_sel:[0,0,1]
	v_pk_mul_f32 v[248:249], v[36:37], v[36:37]
	v_pk_fma_f32 v[248:249], v[38:39], v[38:39], v[248:249]
	v_pk_fma_f32 v[248:249], v[32:33], v[32:33], v[248:249]
	v_pk_fma_f32 v[248:249], v[34:35], v[34:35], v[248:249]
	global_store_dwordx2 v185, v[242:243], s[44:45]
	v_add_f32_e32 v195, v248, v249
	v_pk_mul_f32 v[28:29], v[28:29], v[226:227] op_sel_hi:[1,0]
	v_pk_mul_f32 v[30:31], v[30:31], v[226:227] op_sel_hi:[1,0]
	v_pk_mul_f32 v[24:25], v[24:25], v[226:227] op_sel_hi:[1,0]
	v_pk_mul_f32 v[26:27], v[26:27], v[226:227] op_sel_hi:[1,0]
	v_pk_mul_f32 v[28:29], v[28:29], s[2:3] op_sel_hi:[1,0]
	v_pk_mul_f32 v[30:31], v[30:31], s[2:3] op_sel_hi:[1,0]
	v_pk_mul_f32 v[24:25], v[24:25], s[2:3] op_sel_hi:[1,0]
	v_pk_mul_f32 v[26:27], v[26:27], s[2:3] op_sel_hi:[1,0]
	v_exp_f32_e32 v28, v28
	v_exp_f32_e32 v29, v29
	v_exp_f32_e32 v30, v30
	v_exp_f32_e32 v31, v31
	v_exp_f32_e32 v24, v24
	v_exp_f32_e32 v25, v25
	v_exp_f32_e32 v26, v26
	v_exp_f32_e32 v27, v27
	v_pk_add_f32 v[28:29], v[28:29], s[74:75] op_sel_hi:[1,0]
	v_pk_add_f32 v[30:31], v[30:31], s[74:75] op_sel_hi:[1,0]
	v_pk_add_f32 v[24:25], v[24:25], s[74:75] op_sel_hi:[1,0]
	v_pk_add_f32 v[26:27], v[26:27], s[74:75] op_sel_hi:[1,0]
	v_rcp_f32_e32 v28, v28
	v_rcp_f32_e32 v29, v29
	v_rcp_f32_e32 v30, v30
	v_rcp_f32_e32 v31, v31
	v_rcp_f32_e32 v24, v24
	v_rcp_f32_e32 v25, v25
	v_rcp_f32_e32 v26, v26
	v_rcp_f32_e32 v27, v27
	v_lshlrev_b32_e32 v234, 16, v160
	v_and_b32_e32 v235, 0xffff0000, v160
	v_lshlrev_b32_e32 v236, 16, v161
	v_and_b32_e32 v237, 0xffff0000, v161
	v_lshlrev_b32_e32 v238, 16, v162
	v_and_b32_e32 v239, 0xffff0000, v162
	v_lshlrev_b32_e32 v240, 16, v163
	v_and_b32_e32 v241, 0xffff0000, v163
	v_lshlrev_b32_e32 v242, 16, v172
	v_and_b32_e32 v243, 0xffff0000, v172
	v_lshlrev_b32_e32 v244, 16, v173
	v_and_b32_e32 v245, 0xffff0000, v173
	v_lshlrev_b32_e32 v246, 16, v174
	v_and_b32_e32 v247, 0xffff0000, v174
	v_lshlrev_b32_e32 v248, 16, v175
	v_and_b32_e32 v249, 0xffff0000, v175
	v_pk_fma_f32 v[28:29], v[28:29], v[242:243], v[234:235]
	v_pk_fma_f32 v[30:31], v[30:31], v[244:245], v[236:237]
	v_pk_fma_f32 v[24:25], v[24:25], v[246:247], v[238:239]
	v_pk_fma_f32 v[26:27], v[26:27], v[248:249], v[240:241]
	v_cvt_pk_bf16_f32 v234, v28, v29
	v_cvt_pk_bf16_f32 v235, v30, v31
	v_cvt_pk_bf16_f32 v236, v24, v25
	v_cvt_pk_bf16_f32 v237, v26, v27
	global_store_dwordx4 v183, v[234:237], s[40:41] offset:256
	v_cvt_pk_fp8_f32 v242, v28, v29
	v_cvt_pk_fp8_f32 v243, v24, v25
	v_cvt_pk_fp8_f32 v242, v30, v31 op_sel:[0,0,1]
	v_cvt_pk_fp8_f32 v243, v26, v27 op_sel:[0,0,1]
	v_pk_mul_f32 v[248:249], v[28:29], v[28:29]
	v_pk_fma_f32 v[248:249], v[30:31], v[30:31], v[248:249]
	v_pk_fma_f32 v[248:249], v[24:25], v[24:25], v[248:249]
	v_pk_fma_f32 v[248:249], v[26:27], v[26:27], v[248:249]
	global_store_dwordx2 v185, v[242:243], s[44:45] offset:128
	v_add_f32_e32 v0, v248, v249
	v_add_f32_e32 v224, v195, v0
	s_waitcnt vmcnt(20)
; __device__ __forceinline__ float sigmoidf_(float v) { return __builtin_amdgcn_rcpf(1.0f + __expf(-v)); }
; __device__ __forceinline__ u32x4 pack8(const f32x4 a, const f32x4 b) { u32x4 w; w.x = cvt_pk_bf16(a[0], a[1]); w.y = cvt_pk_bf16(a[2], a[3]); w.z = cvt_pk_bf16(b[0], b[1]); w.w = cvt_pk_bf16(b[2], b[3]); return w; }
; __device__ __forceinline__ void unpack8(const u32x4 w, f32x4& a, f32x4& b) { a[0] = bf_lo(w.x); a[1] = bf_hi(w.x); a[2] = bf_lo(w.y); a[3] = bf_hi(w.y); b[0] = bf_lo(w.z); b[1] = bf_hi(w.z); b[2] = bf_lo(w.w); b[3] = bf_hi(w.w); }
; __device__ __forceinline__ unsigned pack4_fp8(float a, float b, float c, float d) { unsigned w = 0u; w = __builtin_amdgcn_cvt_pk_fp8_f32(a, b, w, false); w = __builtin_amdgcn_cvt_pk_fp8_f32(c, d, w, true); return w; }
;     template <int KIND> __device__ __forceinline__ void run(f32x4 (&acc)[2][2][4][2], const Unit& u, int tid_in) const {
;     ...
;                     for (int ml = 0; ml < 2; ++ml) { const int m = mh * 2 + ml; int row = rbase + ai * 128 + m * 16; asm volatile("" : "+v"(row)); float ss = 0.f; const float r = rs[ai * 4 + m];
; #pragma unroll
;                         for (int bj = 0; bj < 2; ++bj) { const size_t off = (size_t)row * 1024 + u.pn * 256 + bj * 128 + cl; f32x4 a = acc[ai][bj][m][0], b = acc[ai][bj][m][1], p0, p1, x0, x1;
;                             unpack8(pv[ml][bj], p0, p1); unpack8(xv[ml][bj], x0, x1);
; #pragma unroll
;                             for (int j = 0; j < 4; ++j) { a[j] = sigmoidf_(a[j] * r) * p0[j]; b[j] = sigmoidf_(b[j] * r) * p1[j]; }
;                             const f32x4 o0 = x0 + a, o1 = x1 + b;
;                             *(u32x4*)(xb0 + off) = pack8(o0, o1);
;                             { u32x2 w8; w8.x = pack4_fp8(o0[0], o0[1], o0[2], o0[3]); w8.y = pack4_fp8(o1[0], o1[1], o1[2], o1[3]); *(u32x2*)((unsigned char*)zb + (size_t)row * (ZW * 2) + u.pn * 256 + bj * 128 + cl) = w8; }
;                             ss += (o0[0] * o0[0] + o0[1] * o0[1]) + (o0[2] * o0[2] + o0[3] * o0[3]) + (o1[0] * o1[0] + o1[1] * o1[1]) + (o1[2] * o1[2] + o1[3] * o1[3]); }
;                         ss += __shfl_xor(ss, 16); ss += __shfl_xor(ss, 32);
;                         if (fq == 0) ssq0[((size_t)u.pn * T_TOK + row) * 4 + wc] = ss; }
	v_mov_b32_e32 v226, v225
	s_add_u32 s40, s12, 0x58000
	s_addc_u32 s41, s13, 0
	s_add_u32 s44, s10, 0xf2000
	s_addc_u32 s45, s11, 0
	v_pk_mul_f32 v[20:21], v[20:21], v[226:227] op_sel_hi:[1,0]
	v_pk_mul_f32 v[22:23], v[22:23], v[226:227] op_sel_hi:[1,0]
	v_pk_mul_f32 v[16:17], v[16:17], v[226:227] op_sel_hi:[1,0]
	v_pk_mul_f32 v[18:19], v[18:19], v[226:227] op_sel_hi:[1,0]
	v_pk_mul_f32 v[20:21], v[20:21], s[2:3] op_sel_hi:[1,0]
	v_pk_mul_f32 v[22:23], v[22:23], s[2:3] op_sel_hi:[1,0]
	v_pk_mul_f32 v[16:17], v[16:17], s[2:3] op_sel_hi:[1,0]
	v_pk_mul_f32 v[18:19], v[18:19], s[2:3] op_sel_hi:[1,0]
	v_exp_f32_e32 v20, v20
	v_exp_f32_e32 v21, v21
	v_exp_f32_e32 v22, v22
	v_exp_f32_e32 v23, v23
	v_exp_f32_e32 v16, v16
	v_exp_f32_e32 v17, v17
	v_exp_f32_e32 v18, v18
	v_exp_f32_e32 v19, v19
	v_pk_add_f32 v[20:21], v[20:21], s[74:75] op_sel_hi:[1,0]
	v_pk_add_f32 v[22:23], v[22:23], s[74:75] op_sel_hi:[1,0]
	v_pk_add_f32 v[16:17], v[16:17], s[74:75] op_sel_hi:[1,0]
	v_pk_add_f32 v[18:19], v[18:19], s[74:75] op_sel_hi:[1,0]
	v_rcp_f32_e32 v20, v20
	v_rcp_f32_e32 v21, v21
	v_rcp_f32_e32 v22, v22
	v_rcp_f32_e32 v23, v23
	v_rcp_f32_e32 v16, v16
	v_rcp_f32_e32 v17, v17
	v_rcp_f32_e32 v18, v18
	v_rcp_f32_e32 v19, v19
	v_lshlrev_b32_e32 v234, 16, v116
	v_and_b32_e32 v235, 0xffff0000, v116
	v_lshlrev_b32_e32 v236, 16, v117
	v_and_b32_e32 v237, 0xffff0000, v117
	v_lshlrev_b32_e32 v238, 16, v118
	v_and_b32_e32 v239, 0xffff0000, v118
	v_lshlrev_b32_e32 v240, 16, v119
	v_and_b32_e32 v241, 0xffff0000, v119
	v_lshlrev_b32_e32 v242, 16, v108
	v_and_b32_e32 v243, 0xffff0000, v108
	v_lshlrev_b32_e32 v244, 16, v109
	v_and_b32_e32 v245, 0xffff0000, v109
	v_lshlrev_b32_e32 v246, 16, v110
	v_and_b32_e32 v247, 0xffff0000, v110
	v_lshlrev_b32_e32 v248, 16, v111
	v_and_b32_e32 v249, 0xffff0000, v111
	v_pk_fma_f32 v[20:21], v[20:21], v[242:243], v[234:235]
	v_pk_fma_f32 v[22:23], v[22:23], v[244:245], v[236:237]
	v_pk_fma_f32 v[16:17], v[16:17], v[246:247], v[238:239]
	v_pk_fma_f32 v[18:19], v[18:19], v[248:249], v[240:241]
	v_cvt_pk_bf16_f32 v234, v20, v21
	v_cvt_pk_bf16_f32 v235, v22, v23
	v_cvt_pk_bf16_f32 v236, v16, v17
	v_cvt_pk_bf16_f32 v237, v18, v19
	global_store_dwordx4 v183, v[234:237], s[40:41]
	v_cvt_pk_fp8_f32 v242, v20, v21
	v_cvt_pk_fp8_f32 v243, v16, v17
	v_cvt_pk_fp8_f32 v242, v22, v23 op_sel:[0,0,1]
	v_cvt_pk_fp8_f32 v243, v18, v19 op_sel:[0,0,1]
	v_pk_mul_f32 v[248:249], v[20:21], v[20:21]
	v_pk_fma_f32 v[248:249], v[22:23], v[22:23], v[248:249]
	v_pk_fma_f32 v[248:249], v[16:17], v[16:17], v[248:249]
	v_pk_fma_f32 v[248:249], v[18:19], v[18:19], v[248:249]
	global_store_dwordx2 v185, v[242:243], s[44:45]
	v_add_f32_e32 v195, v248, v249
	v_pk_mul_f32 v[12:13], v[12:13], v[226:227] op_sel_hi:[1,0]
	v_pk_mul_f32 v[14:15], v[14:15], v[226:227] op_sel_hi:[1,0]
	v_pk_mul_f32 v[8:9], v[8:9], v[226:227] op_sel_hi:[1,0]
	v_pk_mul_f32 v[10:11], v[10:11], v[226:227] op_sel_hi:[1,0]
	v_pk_mul_f32 v[12:13], v[12:13], s[2:3] op_sel_hi:[1,0]
	v_pk_mul_f32 v[14:15], v[14:15], s[2:3] op_sel_hi:[1,0]
	v_pk_mul_f32 v[8:9], v[8:9], s[2:3] op_sel_hi:[1,0]
	v_pk_mul_f32 v[10:11], v[10:11], s[2:3] op_sel_hi:[1,0]
	v_exp_f32_e32 v12, v12
	v_exp_f32_e32 v13, v13
	v_exp_f32_e32 v14, v14
	v_exp_f32_e32 v15, v15
	v_exp_f32_e32 v8, v8
	v_exp_f32_e32 v9, v9
	v_exp_f32_e32 v10, v10
	v_exp_f32_e32 v11, v11
	v_pk_add_f32 v[12:13], v[12:13], s[74:75] op_sel_hi:[1,0]
	v_pk_add_f32 v[14:15], v[14:15], s[74:75] op_sel_hi:[1,0]
	v_pk_add_f32 v[8:9], v[8:9], s[74:75] op_sel_hi:[1,0]
	v_pk_add_f32 v[10:11], v[10:11], s[74:75] op_sel_hi:[1,0]
	v_rcp_f32_e32 v12, v12
	v_rcp_f32_e32 v13, v13
	v_rcp_f32_e32 v14, v14
	v_rcp_f32_e32 v15, v15
	v_rcp_f32_e32 v8, v8
	v_rcp_f32_e32 v9, v9
	v_rcp_f32_e32 v10, v10
	v_rcp_f32_e32 v11, v11
	v_lshlrev_b32_e32 v234, 16, v112
	v_and_b32_e32 v235, 0xffff0000, v112
	v_lshlrev_b32_e32 v236, 16, v113
	v_and_b32_e32 v237, 0xffff0000, v113
	v_lshlrev_b32_e32 v238, 16, v114
	v_and_b32_e32 v239, 0xffff0000, v114
	v_lshlrev_b32_e32 v240, 16, v115
	v_and_b32_e32 v241, 0xffff0000, v115
	v_lshlrev_b32_e32 v242, 16, v104
	v_and_b32_e32 v243, 0xffff0000, v104
	v_lshlrev_b32_e32 v244, 16, v105
	v_and_b32_e32 v245, 0xffff0000, v105
	v_lshlrev_b32_e32 v246, 16, v106
	v_and_b32_e32 v247, 0xffff0000, v106
	v_lshlrev_b32_e32 v248, 16, v107
	v_and_b32_e32 v249, 0xffff0000, v107
	v_pk_fma_f32 v[12:13], v[12:13], v[242:243], v[234:235]
	v_pk_fma_f32 v[14:15], v[14:15], v[244:245], v[236:237]
	v_pk_fma_f32 v[8:9], v[8:9], v[246:247], v[238:239]
	v_pk_fma_f32 v[10:11], v[10:11], v[248:249], v[240:241]
	v_cvt_pk_bf16_f32 v234, v12, v13
	v_cvt_pk_bf16_f32 v235, v14, v15
	v_cvt_pk_bf16_f32 v236, v8, v9
	v_cvt_pk_bf16_f32 v237, v10, v11
	global_store_dwordx4 v183, v[234:237], s[40:41] offset:256
	v_cvt_pk_fp8_f32 v242, v12, v13
	v_cvt_pk_fp8_f32 v243, v8, v9
	v_cvt_pk_fp8_f32 v242, v14, v15 op_sel:[0,0,1]
	v_cvt_pk_fp8_f32 v243, v10, v11 op_sel:[0,0,1]
	v_pk_mul_f32 v[248:249], v[12:13], v[12:13]
	v_pk_fma_f32 v[248:249], v[14:15], v[14:15], v[248:249]
	v_pk_fma_f32 v[248:249], v[8:9], v[8:9], v[248:249]
	v_pk_fma_f32 v[248:249], v[10:11], v[10:11], v[248:249]
	global_store_dwordx2 v185, v[242:243], s[44:45] offset:128
	v_add_f32_e32 v0, v248, v249
	v_add_f32_e32 v225, v195, v0
	v_xor_b32_e32 v234, 16, v190
	v_xor_b32_e32 v235, 32, v190
	v_lshlrev_b32_e32 v234, 2, v234
	v_lshlrev_b32_e32 v235, 2, v235
	ds_bpermute_b32 v236, v234, v250
	ds_bpermute_b32 v237, v234, v251
	ds_bpermute_b32 v238, v234, v252
	ds_bpermute_b32 v239, v234, v253
	ds_bpermute_b32 v240, v234, v254
	ds_bpermute_b32 v241, v234, v255
	ds_bpermute_b32 v242, v234, v224
	ds_bpermute_b32 v243, v234, v225
	s_waitcnt lgkmcnt(0)
; #define MEMFENCE asm volatile("" ::: "memory")
;     template <int KIND> __device__ __forceinline__ void run(f32x4 (&acc)[2][2][4][2], const Unit& u, int tid_in) const {
;     ...
;                         ss += __shfl_xor(ss, 16); ss += __shfl_xor(ss, 32);
;                         if (fq == 0) ssq0[((size_t)u.pn * T_TOK + row) * 4 + wc] = ss; }
;                     MEMFENCE; }
	v_add_f32_e32 v250, v250, v236
	v_add_f32_e32 v251, v251, v237
	v_add_f32_e32 v252, v252, v238
	v_add_f32_e32 v253, v253, v239
	v_add_f32_e32 v254, v254, v240
	v_add_f32_e32 v255, v255, v241
	v_add_f32_e32 v224, v224, v242
	v_add_f32_e32 v225, v225, v243
	ds_bpermute_b32 v236, v235, v250
	ds_bpermute_b32 v237, v235, v251
	ds_bpermute_b32 v238, v235, v252
	ds_bpermute_b32 v239, v235, v253
	ds_bpermute_b32 v240, v235, v254
	ds_bpermute_b32 v241, v235, v255
	ds_bpermute_b32 v242, v235, v224
	ds_bpermute_b32 v243, v235, v225
	v_and_b32_e32 v0, 15, v180
	v_or_b32_e32 v0, s7, v0
	v_lshlrev_b32_e32 v0, 4, v0
	s_lshl_b32 s74, s53, 2
	v_add_u32_e32 v0, s74, v0
	s_ashr_i32 s7, s6, 31
	s_lshl_b64 s[4:5], s[6:7], 19
	s_add_u32 s4, s39, s4
	s_addc_u32 s5, s42, s5
	v_bfe_u32 v195, v180, 4, 2
	v_cmp_eq_u32_e64 s[40:41], 0, v195
	s_waitcnt lgkmcnt(0)
	v_add_f32_e32 v250, v250, v236
	v_add_f32_e32 v251, v251, v237
	v_add_f32_e32 v252, v252, v238
	v_add_f32_e32 v253, v253, v239
	v_add_f32_e32 v254, v254, v240
	v_add_f32_e32 v255, v255, v241
	v_add_f32_e32 v224, v224, v242
	v_add_f32_e32 v225, v225, v243
	v_readlane_b32 s44, v230, 7
	v_readlane_b32 s45, v230, 8
	s_and_saveexec_b64 s[2:3], s[40:41]
	global_store_dword v0, v250, s[4:5]
	global_store_dword v0, v251, s[4:5] offset:256
	global_store_dword v0, v252, s[4:5] offset:512
	global_store_dword v0, v253, s[4:5] offset:768
	global_store_dword v0, v254, s[4:5] offset:2048
	global_store_dword v0, v255, s[4:5] offset:2304
	global_store_dword v0, v224, s[4:5] offset:2560
	global_store_dword v0, v225, s[4:5] offset:2816
	s_branch .LBB0_1277
